# adds: in-proj column tiles rotated per round (balances epilogue types per workgroup), weight-transpose scale loads issued together, QK-norm lane exchanges via permlane swaps, in-proj rstd values preco
# speedup vs baseline: 1.0451x; 1.0133x over previous
.LBB0_47:
	s_load_dwordx2 s[48:49], s[20:21], 0x18
	s_ashr_i32 s18, s22, 11
	s_ashr_i32 s19, s18, 31
	s_lshl_b64 s[50:51], s[18:19], 25
	v_mov_b32_e32 v43, v67
	s_waitcnt lgkmcnt(0)
	s_add_u32 s23, s48, s50
	s_addc_u32 s48, s49, s51
	s_and_b32 s4, s22, 0x7c0
	s_lshl_b32 s22, s22, 6
	s_and_b32 s47, s22, 0xfc0
	s_lshl_b32 s22, s47, 2
	s_add_u32 s22, s23, s22
	v_or_b32_e32 v118, s4, v76
	s_addc_u32 s23, s48, 0
	v_lshl_add_u64 v[40:41], s[22:23], 0, v[66:67]
	v_lshlrev_b32_e32 v42, 14, v118
	v_lshl_add_u64 v[0:1], v[40:41], 0, v[42:43]
	v_or_b32_e32 v2, 0x10000, v42
	v_mov_b32_e32 v3, v67
	v_or_b32_e32 v8, 0x20000, v42
	v_mov_b32_e32 v9, v67
	v_or_b32_e32 v10, 0x30000, v42
	v_mov_b32_e32 v11, v67
	v_or_b32_e32 v16, 0x40000, v42
	v_mov_b32_e32 v17, v67
	v_or_b32_e32 v18, 0x50000, v42
	v_mov_b32_e32 v19, v67
	v_or_b32_e32 v24, 0x60000, v42
	v_mov_b32_e32 v25, v67
	v_or_b32_e32 v26, 0x70000, v42
	v_mov_b32_e32 v27, v67
	v_or_b32_e32 v32, 0x80000, v42
	v_mov_b32_e32 v33, v67
	v_or_b32_e32 v34, 0x90000, v42
	v_mov_b32_e32 v35, v67
	v_or_b32_e32 v44, 0xa0000, v42
	v_mov_b32_e32 v45, v67
	v_or_b32_e32 v46, 0xb0000, v42
	v_mov_b32_e32 v47, v67
	v_or_b32_e32 v48, 0xc0000, v42
	v_mov_b32_e32 v49, v67
	v_or_b32_e32 v50, 0xd0000, v42
	v_mov_b32_e32 v51, v67
	v_or_b32_e32 v52, 0xe0000, v42
	v_mov_b32_e32 v53, v67
	v_or_b32_e32 v42, 0xf0000, v42
	v_lshl_add_u64 v[2:3], v[40:41], 0, v[2:3]
	v_lshl_add_u64 v[8:9], v[40:41], 0, v[8:9]
	v_lshl_add_u64 v[10:11], v[40:41], 0, v[10:11]
	v_lshl_add_u64 v[16:17], v[40:41], 0, v[16:17]
	v_lshl_add_u64 v[18:19], v[40:41], 0, v[18:19]
	v_lshl_add_u64 v[24:25], v[40:41], 0, v[24:25]
	v_lshl_add_u64 v[26:27], v[40:41], 0, v[26:27]
	v_lshl_add_u64 v[32:33], v[40:41], 0, v[32:33]
	v_lshl_add_u64 v[34:35], v[40:41], 0, v[34:35]
	v_lshl_add_u64 v[44:45], v[40:41], 0, v[44:45]
	v_lshl_add_u64 v[46:47], v[40:41], 0, v[46:47]
	v_lshl_add_u64 v[48:49], v[40:41], 0, v[48:49]
	v_lshl_add_u64 v[50:51], v[40:41], 0, v[50:51]
	v_lshl_add_u64 v[120:121], v[40:41], 0, v[52:53]
	v_lshl_add_u64 v[40:41], v[40:41], 0, v[42:43]
	global_load_dwordx4 v[4:7], v[0:1], off
	s_nop 0
	global_load_dwordx4 v[0:3], v[2:3], off
	s_nop 0
	global_load_dwordx4 v[12:15], v[8:9], off
	s_nop 0
	global_load_dwordx4 v[8:11], v[10:11], off
	s_nop 0
	global_load_dwordx4 v[20:23], v[16:17], off
	s_nop 0
	global_load_dwordx4 v[16:19], v[18:19], off
	s_nop 0
	global_load_dwordx4 v[28:31], v[24:25], off
	s_nop 0
	global_load_dwordx4 v[24:27], v[26:27], off
	s_nop 0
	global_load_dwordx4 v[36:39], v[32:33], off
	s_nop 0
	global_load_dwordx4 v[32:35], v[34:35], off
	s_nop 0
	global_load_dwordx4 v[60:63], v[44:45], off
	global_load_dwordx4 v[56:59], v[46:47], off
	global_load_dwordx4 v[52:55], v[48:49], off
	s_nop 0
	global_load_dwordx4 v[48:51], v[50:51], off
	s_nop 0
	global_load_dwordx4 v[44:47], v[120:121], off
	s_nop 0
	global_load_dwordx4 v[40:43], v[40:41], off
	s_andn2_b64 vcc, exec, s[16:17]
	s_cbranch_vccnz .LBB0_25
	s_mul_i32 s22, s18, 0x1800
	s_ashr_i32 s23, s22, 31
	s_lshl_b64 s[22:23], s[22:23], 2
	s_add_u32 s22, s6, s22
	s_addc_u32 s23, s7, s23
	v_lshlrev_b32_e32 v119, 2, v118
	global_load_dword v160, v119, s[22:23]
	global_load_dword v161, v119, s[22:23] offset:16
	global_load_dword v162, v119, s[22:23] offset:32
	global_load_dword v163, v119, s[22:23] offset:48
	global_load_dword v164, v119, s[22:23] offset:64
	global_load_dword v165, v119, s[22:23] offset:80
	global_load_dword v166, v119, s[22:23] offset:96
	global_load_dword v167, v119, s[22:23] offset:112
	global_load_dword v168, v119, s[22:23] offset:128
	global_load_dword v169, v119, s[22:23] offset:144
	global_load_dword v170, v119, s[22:23] offset:160
	global_load_dword v171, v119, s[22:23] offset:176
	global_load_dword v172, v119, s[22:23] offset:192
	global_load_dword v173, v119, s[22:23] offset:208
	global_load_dword v174, v119, s[22:23] offset:224
	global_load_dword v175, v119, s[22:23] offset:240
	s_waitcnt vmcnt(0)
	v_mov_b32_e32 v118, v160
	s_waitcnt vmcnt(0)
	v_pk_mul_f32 v[6:7], v[6:7], v[118:119] op_sel_hi:[1,0]
	v_pk_mul_f32 v[4:5], v[4:5], v[118:119] op_sel_hi:[1,0]
	v_mov_b32_e32 v118, v161
	s_waitcnt vmcnt(0)
	v_pk_mul_f32 v[2:3], v[2:3], v[118:119] op_sel_hi:[1,0]
	v_pk_mul_f32 v[0:1], v[0:1], v[118:119] op_sel_hi:[1,0]
	v_mov_b32_e32 v118, v162
	s_waitcnt vmcnt(0)
	v_pk_mul_f32 v[14:15], v[14:15], v[118:119] op_sel_hi:[1,0]
	v_pk_mul_f32 v[12:13], v[12:13], v[118:119] op_sel_hi:[1,0]
	v_mov_b32_e32 v118, v163
	s_waitcnt vmcnt(0)
	v_pk_mul_f32 v[10:11], v[10:11], v[118:119] op_sel_hi:[1,0]
	v_pk_mul_f32 v[8:9], v[8:9], v[118:119] op_sel_hi:[1,0]
	v_mov_b32_e32 v118, v164
	s_waitcnt vmcnt(0)
	v_pk_mul_f32 v[22:23], v[22:23], v[118:119] op_sel_hi:[1,0]
	v_pk_mul_f32 v[20:21], v[20:21], v[118:119] op_sel_hi:[1,0]
	v_mov_b32_e32 v118, v165
	s_waitcnt vmcnt(0)
	v_pk_mul_f32 v[18:19], v[18:19], v[118:119] op_sel_hi:[1,0]
	v_pk_mul_f32 v[16:17], v[16:17], v[118:119] op_sel_hi:[1,0]
	v_mov_b32_e32 v118, v166
	s_waitcnt vmcnt(0)
	v_pk_mul_f32 v[30:31], v[30:31], v[118:119] op_sel_hi:[1,0]
	v_pk_mul_f32 v[28:29], v[28:29], v[118:119] op_sel_hi:[1,0]
	v_mov_b32_e32 v118, v167
	s_waitcnt vmcnt(0)
	v_pk_mul_f32 v[26:27], v[26:27], v[118:119] op_sel_hi:[1,0]
	v_pk_mul_f32 v[24:25], v[24:25], v[118:119] op_sel_hi:[1,0]
	v_mov_b32_e32 v118, v168
	s_waitcnt vmcnt(0)
	v_pk_mul_f32 v[38:39], v[38:39], v[118:119] op_sel_hi:[1,0]
	v_pk_mul_f32 v[36:37], v[36:37], v[118:119] op_sel_hi:[1,0]
	v_mov_b32_e32 v118, v169
	s_waitcnt vmcnt(0)
	v_pk_mul_f32 v[34:35], v[34:35], v[118:119] op_sel_hi:[1,0]
	v_pk_mul_f32 v[32:33], v[32:33], v[118:119] op_sel_hi:[1,0]
	v_mov_b32_e32 v118, v170
	s_waitcnt vmcnt(0)
	v_pk_mul_f32 v[62:63], v[62:63], v[118:119] op_sel_hi:[1,0]
	v_pk_mul_f32 v[60:61], v[60:61], v[118:119] op_sel_hi:[1,0]
	v_mov_b32_e32 v118, v171
	s_waitcnt vmcnt(0)
	v_pk_mul_f32 v[58:59], v[58:59], v[118:119] op_sel_hi:[1,0]
	v_pk_mul_f32 v[56:57], v[56:57], v[118:119] op_sel_hi:[1,0]
	v_mov_b32_e32 v118, v172
	s_waitcnt vmcnt(0)
	v_pk_mul_f32 v[54:55], v[54:55], v[118:119] op_sel_hi:[1,0]
	v_pk_mul_f32 v[52:53], v[52:53], v[118:119] op_sel_hi:[1,0]
	v_mov_b32_e32 v118, v173
	s_waitcnt vmcnt(0)
	v_pk_mul_f32 v[50:51], v[50:51], v[118:119] op_sel_hi:[1,0]
	v_pk_mul_f32 v[48:49], v[48:49], v[118:119] op_sel_hi:[1,0]
	v_mov_b32_e32 v118, v174
	s_waitcnt vmcnt(0)
	v_pk_mul_f32 v[46:47], v[46:47], v[118:119] op_sel_hi:[1,0]
	v_pk_mul_f32 v[44:45], v[44:45], v[118:119] op_sel_hi:[1,0]
	v_mov_b32_e32 v118, v175
	s_waitcnt vmcnt(0)
	v_pk_mul_f32 v[42:43], v[42:43], v[118:119] op_sel_hi:[1,0]
	v_pk_mul_f32 v[40:41], v[40:41], v[118:119] op_sel_hi:[1,0]
	s_branch .LBB0_25

.LBB0_145:
	s_load_dwordx2 s[62:63], s[2:3], 0x18
	s_ashr_i32 s16, s18, 11
	s_ashr_i32 s17, s16, 31
	s_lshl_b64 s[64:65], s[16:17], 25
	v_mov_b32_e32 v59, v65
	s_waitcnt lgkmcnt(0)
	s_add_u32 s19, s62, s64
	s_addc_u32 s62, s63, s65
	s_and_b32 s8, s18, 0x7c0
	s_lshl_b32 s18, s60, 6
	s_and_b32 s61, s18, 0xfc0
	s_lshl_b32 s18, s61, 2
	s_add_u32 s18, s19, s18
	v_or_b32_e32 v73, s8, v88
	s_addc_u32 s19, s62, 0
	v_lshl_add_u64 v[56:57], s[18:19], 0, v[64:65]
	v_lshlrev_b32_e32 v58, 14, v73
	v_lshl_add_u64 v[0:1], v[56:57], 0, v[58:59]
	v_or_b32_e32 v2, 0x10000, v58
	v_mov_b32_e32 v3, v65
	v_or_b32_e32 v8, 0x20000, v58
	v_mov_b32_e32 v9, v65
	v_or_b32_e32 v10, 0x30000, v58
	v_mov_b32_e32 v11, v65
	v_or_b32_e32 v16, 0x40000, v58
	v_mov_b32_e32 v17, v65
	v_or_b32_e32 v18, 0x50000, v58
	v_mov_b32_e32 v19, v65
	v_or_b32_e32 v24, 0x60000, v58
	v_mov_b32_e32 v25, v65
	v_or_b32_e32 v26, 0x70000, v58
	v_mov_b32_e32 v27, v65
	v_or_b32_e32 v32, 0x80000, v58
	v_mov_b32_e32 v33, v65
	v_or_b32_e32 v34, 0x90000, v58
	v_mov_b32_e32 v35, v65
	v_or_b32_e32 v40, 0xa0000, v58
	v_mov_b32_e32 v41, v65
	v_or_b32_e32 v42, 0xb0000, v58
	v_mov_b32_e32 v43, v65
	v_or_b32_e32 v48, 0xc0000, v58
	v_mov_b32_e32 v49, v65
	v_or_b32_e32 v50, 0xd0000, v58
	v_mov_b32_e32 v51, v65
	v_or_b32_e32 v60, 0xe0000, v58
	v_mov_b32_e32 v61, v65
	v_or_b32_e32 v58, 0xf0000, v58
	v_lshl_add_u64 v[2:3], v[56:57], 0, v[2:3]
	v_lshl_add_u64 v[8:9], v[56:57], 0, v[8:9]
	v_lshl_add_u64 v[10:11], v[56:57], 0, v[10:11]
	v_lshl_add_u64 v[16:17], v[56:57], 0, v[16:17]
	v_lshl_add_u64 v[18:19], v[56:57], 0, v[18:19]
	v_lshl_add_u64 v[24:25], v[56:57], 0, v[24:25]
	v_lshl_add_u64 v[26:27], v[56:57], 0, v[26:27]
	v_lshl_add_u64 v[32:33], v[56:57], 0, v[32:33]
	v_lshl_add_u64 v[34:35], v[56:57], 0, v[34:35]
	v_lshl_add_u64 v[40:41], v[56:57], 0, v[40:41]
	v_lshl_add_u64 v[42:43], v[56:57], 0, v[42:43]
	v_lshl_add_u64 v[48:49], v[56:57], 0, v[48:49]
	v_lshl_add_u64 v[50:51], v[56:57], 0, v[50:51]
	v_lshl_add_u64 v[60:61], v[56:57], 0, v[60:61]
	v_lshl_add_u64 v[56:57], v[56:57], 0, v[58:59]
	global_load_dwordx4 v[4:7], v[0:1], off
	s_nop 0
	global_load_dwordx4 v[0:3], v[2:3], off
	s_nop 0
	global_load_dwordx4 v[12:15], v[8:9], off
	s_nop 0
	global_load_dwordx4 v[8:11], v[10:11], off
	s_nop 0
	global_load_dwordx4 v[20:23], v[16:17], off
	s_nop 0
	global_load_dwordx4 v[16:19], v[18:19], off
	s_nop 0
	global_load_dwordx4 v[28:31], v[24:25], off
	s_nop 0
	global_load_dwordx4 v[24:27], v[26:27], off
	s_nop 0
	global_load_dwordx4 v[36:39], v[32:33], off
	s_nop 0
	global_load_dwordx4 v[32:35], v[34:35], off
	s_nop 0
	global_load_dwordx4 v[44:47], v[40:41], off
	s_nop 0
	global_load_dwordx4 v[40:43], v[42:43], off
	s_nop 0
	global_load_dwordx4 v[52:55], v[48:49], off
	s_nop 0
	global_load_dwordx4 v[48:51], v[50:51], off
	s_nop 0
	global_load_dwordx4 v[60:63], v[60:61], off
	s_nop 0
	global_load_dwordx4 v[56:59], v[56:57], off
	s_andn2_b64 vcc, exec, s[14:15]
	s_cbranch_vccnz .LBB0_124
	s_mul_i32 s18, s16, 0x1800
	s_ashr_i32 s19, s18, 31
	s_lshl_b64 s[18:19], s[18:19], 2
	s_add_u32 s18, s6, s18
	s_addc_u32 s19, s7, s19
	v_lshlrev_b32_e32 v73, 2, v73
	global_load_dword v160, v73, s[18:19]
	global_load_dword v161, v73, s[18:19] offset:16
	global_load_dword v162, v73, s[18:19] offset:32
	global_load_dword v163, v73, s[18:19] offset:48
	global_load_dword v164, v73, s[18:19] offset:64
	global_load_dword v165, v73, s[18:19] offset:80
	global_load_dword v166, v73, s[18:19] offset:96
	global_load_dword v167, v73, s[18:19] offset:112
	global_load_dword v168, v73, s[18:19] offset:128
	global_load_dword v169, v73, s[18:19] offset:144
	global_load_dword v170, v73, s[18:19] offset:160
	global_load_dword v171, v73, s[18:19] offset:176
	global_load_dword v172, v73, s[18:19] offset:192
	global_load_dword v173, v73, s[18:19] offset:208
	global_load_dword v174, v73, s[18:19] offset:224
	global_load_dword v175, v73, s[18:19] offset:240
	s_waitcnt vmcnt(0)
	v_mov_b32_e32 v126, v160
	s_waitcnt vmcnt(0)
	v_pk_mul_f32 v[6:7], v[6:7], v[126:127] op_sel_hi:[1,0]
	v_pk_mul_f32 v[4:5], v[4:5], v[126:127] op_sel_hi:[1,0]
	v_mov_b32_e32 v126, v161
	s_waitcnt vmcnt(0)
	v_pk_mul_f32 v[2:3], v[2:3], v[126:127] op_sel_hi:[1,0]
	v_pk_mul_f32 v[0:1], v[0:1], v[126:127] op_sel_hi:[1,0]
	v_mov_b32_e32 v126, v162
	s_waitcnt vmcnt(0)
	v_pk_mul_f32 v[14:15], v[14:15], v[126:127] op_sel_hi:[1,0]
	v_pk_mul_f32 v[12:13], v[12:13], v[126:127] op_sel_hi:[1,0]
	v_mov_b32_e32 v126, v163
	s_waitcnt vmcnt(0)
	v_pk_mul_f32 v[10:11], v[10:11], v[126:127] op_sel_hi:[1,0]
	v_pk_mul_f32 v[8:9], v[8:9], v[126:127] op_sel_hi:[1,0]
	v_mov_b32_e32 v126, v164
	s_waitcnt vmcnt(0)
	v_pk_mul_f32 v[22:23], v[22:23], v[126:127] op_sel_hi:[1,0]
	v_pk_mul_f32 v[20:21], v[20:21], v[126:127] op_sel_hi:[1,0]
	v_mov_b32_e32 v126, v165
	s_waitcnt vmcnt(0)
	v_pk_mul_f32 v[18:19], v[18:19], v[126:127] op_sel_hi:[1,0]
	v_pk_mul_f32 v[16:17], v[16:17], v[126:127] op_sel_hi:[1,0]
	v_mov_b32_e32 v126, v166
	s_waitcnt vmcnt(0)
	v_pk_mul_f32 v[30:31], v[30:31], v[126:127] op_sel_hi:[1,0]
	v_pk_mul_f32 v[28:29], v[28:29], v[126:127] op_sel_hi:[1,0]
	v_mov_b32_e32 v126, v167
	s_waitcnt vmcnt(0)
	v_pk_mul_f32 v[26:27], v[26:27], v[126:127] op_sel_hi:[1,0]
	v_pk_mul_f32 v[24:25], v[24:25], v[126:127] op_sel_hi:[1,0]
	v_mov_b32_e32 v126, v168
	s_waitcnt vmcnt(0)
	v_pk_mul_f32 v[38:39], v[38:39], v[126:127] op_sel_hi:[1,0]
	v_pk_mul_f32 v[36:37], v[36:37], v[126:127] op_sel_hi:[1,0]
	v_mov_b32_e32 v126, v169
	s_waitcnt vmcnt(0)
	v_pk_mul_f32 v[34:35], v[34:35], v[126:127] op_sel_hi:[1,0]
	v_pk_mul_f32 v[32:33], v[32:33], v[126:127] op_sel_hi:[1,0]
	v_mov_b32_e32 v126, v170
	s_waitcnt vmcnt(0)
	v_pk_mul_f32 v[46:47], v[46:47], v[126:127] op_sel_hi:[1,0]
	v_pk_mul_f32 v[44:45], v[44:45], v[126:127] op_sel_hi:[1,0]
	v_mov_b32_e32 v126, v171
	s_waitcnt vmcnt(0)
	v_pk_mul_f32 v[42:43], v[42:43], v[126:127] op_sel_hi:[1,0]
	v_pk_mul_f32 v[40:41], v[40:41], v[126:127] op_sel_hi:[1,0]
	v_mov_b32_e32 v126, v172
	s_waitcnt vmcnt(0)
	v_pk_mul_f32 v[54:55], v[54:55], v[126:127] op_sel_hi:[1,0]
	v_pk_mul_f32 v[52:53], v[52:53], v[126:127] op_sel_hi:[1,0]
	v_mov_b32_e32 v126, v173
	s_waitcnt vmcnt(0)
	v_pk_mul_f32 v[50:51], v[50:51], v[126:127] op_sel_hi:[1,0]
	v_pk_mul_f32 v[48:49], v[48:49], v[126:127] op_sel_hi:[1,0]
	v_mov_b32_e32 v126, v174
	s_waitcnt vmcnt(0)
	v_pk_mul_f32 v[62:63], v[62:63], v[126:127] op_sel_hi:[1,0]
	v_pk_mul_f32 v[60:61], v[60:61], v[126:127] op_sel_hi:[1,0]
	v_mov_b32_e32 v126, v175
	s_waitcnt vmcnt(0)
	v_pk_mul_f32 v[58:59], v[58:59], v[126:127] op_sel_hi:[1,0]
	v_pk_mul_f32 v[56:57], v[56:57], v[126:127] op_sel_hi:[1,0]
	s_branch .LBB0_124

.LBB0_182:
	s_add_i32 s70, s87, 1
	s_ashr_i32 s71, s70, 31
	s_lshl_b64 s[2:3], s[70:71], 7
	s_or_b64 s[2:3], s[2:3], s[72:73]
	v_cmp_ge_i64_e64 s[4:5], s[2:3], v[222:223]
	s_mov_b64 s[62:63], s[72:73]
	v_cmp_lt_i64_e64 s[8:9], s[2:3], v[222:223]
	s_and_b64 vcc, exec, s[4:5]
	s_cbranch_vccnz .LBB0_184
	s_ashr_i32 s3, s2, 31
	s_lshr_b32 s3, s3, 29
	s_add_i32 s3, s2, s3
	s_ashr_i32 s6, s3, 3
	s_and_b32 s3, s3, -8
	s_sub_i32 s2, s2, s3
	s_waitcnt vmcnt(0)
	v_mov_b32_e32 v128, s2
	v_alignbit_b32 v128, s49, v128, 31
	v_readlane_b32 s7, v255, 1
	v_readfirstlane_b32 s3, v128
	s_mul_i32 s2, s3, s2
	s_add_i32 s2, s2, s6
	s_abs_i32 s6, s2
	s_mul_hi_u32 s7, s6, s7
	s_mul_i32 s10, s7, s88
	s_sub_i32 s6, s6, s10
	s_ashr_i32 s3, s2, 31
	s_add_i32 s10, s7, 1
	s_sub_i32 s11, s6, s88
	s_cmp_ge_u32 s6, s88
	s_cselect_b32 s7, s10, s7
	s_cselect_b32 s6, s11, s6
	s_add_i32 s10, s7, 1
	s_cmp_ge_u32 s6, s88
	s_cselect_b32 s6, s10, s7
	s_xor_b32 s6, s6, s3
	s_sub_i32 s3, s6, s3
	s_lshl_b32 s6, s3, 3
	s_sub_i32 s7, 16, s6
	s_min_i32 s7, s7, 8
	s_abs_i32 s10, s7
	v_cvt_f32_u32_e32 v128, s10
	s_sub_i32 s12, 0, s10
	s_mul_i32 s3, s3, s88
	s_sub_i32 s2, s2, s3
	v_rcp_iflag_f32_e32 v128, v128
	s_abs_i32 s11, s2
	s_xor_b32 s3, s2, s7
	s_ashr_i32 s3, s3, 31
	v_mul_f32_e32 v128, 0x4f7ffffe, v128
	v_cvt_u32_f32_e32 v128, v128
	s_nop 0
	v_readfirstlane_b32 s13, v128
	s_mul_i32 s12, s12, s13
	s_mul_hi_u32 s12, s13, s12
	s_add_i32 s13, s13, s12
	s_mul_hi_u32 s12, s11, s13
	s_mul_i32 s13, s12, s10
	s_sub_i32 s11, s11, s13
	s_add_i32 s13, s12, 1
	s_sub_i32 s24, s11, s10
	s_cmp_ge_u32 s11, s10
	s_cselect_b32 s12, s13, s12
	s_cselect_b32 s11, s24, s11
	s_add_i32 s13, s12, 1
	s_cmp_ge_u32 s11, s10
	s_cselect_b32 s10, s13, s12
	s_xor_b32 s10, s10, s3
	s_sub_i32 s33, s10, s3
	s_mul_i32 s3, s33, s7
	s_sub_i32 s2, s2, s3
	s_add_i32 s3, s6, s60
	s_add_i32 s50, s3, s2
	s_lshl_b32 s2, s70, 3
	s_add_i32 s33, s33, s2
	s_add_i32 s3, s49, -1
	s_and_b32 s33, s33, s3

.LBB0_299:
	s_andn2_b64 vcc, exec, s[2:3]
	s_cbranch_vccnz .LBB0_392
	s_lshl_b32 s2, s46, 8
	s_ashr_i32 s24, s46, 3
	s_and_b32 s71, s2, 0x700
	s_cmp_eq_u32 s24, s48
	s_cselect_b64 s[2:3], -1, 0
	s_cmp_lg_u32 s24, s48
	s_cselect_b64 s[8:9], -1, 0
	s_and_b64 s[10:11], s[8:9], exec
	s_cselect_b32 s10, s24, 3
	s_ashr_i32 s11, s10, 31
	s_lshl_b64 s[10:11], s[10:11], 25
	v_readlane_b32 s12, v254, 61
	s_add_u32 s90, s12, s10
	v_readlane_b32 s10, v254, 62
	s_addc_u32 s91, s10, s11
	s_cmp_lt_i32 s24, 2
	v_readlane_b32 s12, v254, 38
	s_cselect_b64 s[10:11], -1, 0
	v_readlane_b32 s13, v254, 39
	s_and_b64 s[12:13], s[12:13], s[10:11]
	s_mov_b64 s[10:11], -1
	s_and_b64 vcc, exec, s[12:13]
	v_ashrrev_i32_e32 v225, 31, v224
	s_cbranch_vccnz .LBB0_358
	v_mov_b32_e32 v171, v224
	v_lshlrev_b32_e32 v171, 5, v171
	global_load_dwordx4 v[172:175], v171, s[44:45]
	global_load_dwordx4 v[176:179], v171, s[44:45] offset:16
	v_add_u32_e32 v171, 0x10, v224
	v_lshlrev_b32_e32 v171, 5, v171
	global_load_dwordx4 v[180:183], v171, s[44:45]
	global_load_dwordx4 v[184:187], v171, s[44:45] offset:16
	v_add_u32_e32 v171, 0x20, v224
	v_lshlrev_b32_e32 v171, 5, v171
	global_load_dwordx4 v[188:191], v171, s[44:45]
	global_load_dwordx4 v[192:195], v171, s[44:45] offset:16
	v_add_u32_e32 v171, 0x30, v224
	v_lshlrev_b32_e32 v171, 5, v171
	global_load_dwordx4 v[196:199], v171, s[44:45]
	global_load_dwordx4 v[200:203], v171, s[44:45] offset:16
	s_waitcnt vmcnt(0)
	v_add_f32_e32 v172, v172, v173
	v_add_f32_e32 v174, v174, v175
	v_add_f32_e32 v176, v176, v177
	v_add_f32_e32 v178, v178, v179
	v_add_f32_e32 v172, v172, v174
	v_add_f32_e32 v176, v176, v178
	v_add_f32_e32 v172, v172, v176
	v_mov_b32_e32 v173, 0x358637bd
	v_fmamk_f32 v172, v172, 0x3a000000, v173
	v_mul_f32_e32 v173, 0x4b800000, v172
	v_cmp_gt_f32_e32 vcc, 0x800000, v172
	s_nop 1
	v_cndmask_b32_e32 v172, v172, v173, vcc
	v_rsq_f32_e32 v172, v172
	s_nop 0
	v_mul_f32_e32 v173, 0x45800000, v172
	v_cndmask_b32_e32 v204, v172, v173, vcc
	v_add_f32_e32 v180, v180, v181
	v_add_f32_e32 v182, v182, v183
	v_add_f32_e32 v184, v184, v185
	v_add_f32_e32 v186, v186, v187
	v_add_f32_e32 v180, v180, v182
	v_add_f32_e32 v184, v184, v186
	v_add_f32_e32 v180, v180, v184
	v_mov_b32_e32 v181, 0x358637bd
	v_fmamk_f32 v180, v180, 0x3a000000, v181
	v_mul_f32_e32 v181, 0x4b800000, v180
	v_cmp_gt_f32_e32 vcc, 0x800000, v180
	s_nop 1
	v_cndmask_b32_e32 v180, v180, v181, vcc
	v_rsq_f32_e32 v180, v180
	s_nop 0
	v_mul_f32_e32 v181, 0x45800000, v180
	v_cndmask_b32_e32 v205, v180, v181, vcc
	v_add_f32_e32 v188, v188, v189
	v_add_f32_e32 v190, v190, v191
	v_add_f32_e32 v192, v192, v193
	v_add_f32_e32 v194, v194, v195
	v_add_f32_e32 v188, v188, v190
	v_add_f32_e32 v192, v192, v194
	v_add_f32_e32 v188, v188, v192
	v_mov_b32_e32 v189, 0x358637bd
	v_fmamk_f32 v188, v188, 0x3a000000, v189
	v_mul_f32_e32 v189, 0x4b800000, v188
	v_cmp_gt_f32_e32 vcc, 0x800000, v188
	s_nop 1
	v_cndmask_b32_e32 v188, v188, v189, vcc
	v_rsq_f32_e32 v188, v188
	s_nop 0
	v_mul_f32_e32 v189, 0x45800000, v188
	v_cndmask_b32_e32 v206, v188, v189, vcc
	v_add_f32_e32 v196, v196, v197
	v_add_f32_e32 v198, v198, v199
	v_add_f32_e32 v200, v200, v201
	v_add_f32_e32 v202, v202, v203
	v_add_f32_e32 v196, v196, v198
	v_add_f32_e32 v200, v200, v202
	v_add_f32_e32 v196, v196, v200
	v_mov_b32_e32 v197, 0x358637bd
	v_fmamk_f32 v196, v196, 0x3a000000, v197
	v_mul_f32_e32 v197, 0x4b800000, v196
	v_cmp_gt_f32_e32 vcc, 0x800000, v196
	s_nop 1
	v_cndmask_b32_e32 v196, v196, v197, vcc
	v_rsq_f32_e32 v196, v196
	s_nop 0
	v_mul_f32_e32 v197, 0x45800000, v196
	v_cndmask_b32_e32 v207, v196, v197, vcc
	v_add_u32_e32 v171, 0x80, v224
	v_lshlrev_b32_e32 v171, 5, v171
	global_load_dwordx4 v[172:175], v171, s[44:45]
	global_load_dwordx4 v[176:179], v171, s[44:45] offset:16
	v_add_u32_e32 v171, 0x90, v224
	v_lshlrev_b32_e32 v171, 5, v171
	global_load_dwordx4 v[180:183], v171, s[44:45]
	global_load_dwordx4 v[184:187], v171, s[44:45] offset:16
	v_add_u32_e32 v171, 0xa0, v224
	v_lshlrev_b32_e32 v171, 5, v171
	global_load_dwordx4 v[188:191], v171, s[44:45]
	global_load_dwordx4 v[192:195], v171, s[44:45] offset:16
	v_add_u32_e32 v171, 0xb0, v224
	v_lshlrev_b32_e32 v171, 5, v171
	global_load_dwordx4 v[196:199], v171, s[44:45]
	global_load_dwordx4 v[200:203], v171, s[44:45] offset:16
	s_waitcnt vmcnt(0)
	v_add_f32_e32 v172, v172, v173
	v_add_f32_e32 v174, v174, v175
	v_add_f32_e32 v176, v176, v177
	v_add_f32_e32 v178, v178, v179
	v_add_f32_e32 v172, v172, v174
	v_add_f32_e32 v176, v176, v178
	v_add_f32_e32 v172, v172, v176
	v_mov_b32_e32 v173, 0x358637bd
	v_fmamk_f32 v172, v172, 0x3a000000, v173
	v_mul_f32_e32 v173, 0x4b800000, v172
	v_cmp_gt_f32_e32 vcc, 0x800000, v172
	s_nop 1
	v_cndmask_b32_e32 v172, v172, v173, vcc
	v_rsq_f32_e32 v172, v172
	s_nop 0
	v_mul_f32_e32 v173, 0x45800000, v172
	v_cndmask_b32_e32 v172, v172, v173, vcc
	v_add_f32_e32 v180, v180, v181
	v_add_f32_e32 v182, v182, v183
	v_add_f32_e32 v184, v184, v185
	v_add_f32_e32 v186, v186, v187
	v_add_f32_e32 v180, v180, v182
	v_add_f32_e32 v184, v184, v186
	v_add_f32_e32 v180, v180, v184
	v_mov_b32_e32 v181, 0x358637bd
	v_fmamk_f32 v180, v180, 0x3a000000, v181
	v_mul_f32_e32 v181, 0x4b800000, v180
	v_cmp_gt_f32_e32 vcc, 0x800000, v180
	s_nop 1
	v_cndmask_b32_e32 v180, v180, v181, vcc
	v_rsq_f32_e32 v180, v180
	s_nop 0
	v_mul_f32_e32 v181, 0x45800000, v180
	v_cndmask_b32_e32 v180, v180, v181, vcc
	v_add_f32_e32 v188, v188, v189
	v_add_f32_e32 v190, v190, v191
	v_add_f32_e32 v192, v192, v193
	v_add_f32_e32 v194, v194, v195
	v_add_f32_e32 v188, v188, v190
	v_add_f32_e32 v192, v192, v194
	v_add_f32_e32 v188, v188, v192
	v_mov_b32_e32 v189, 0x358637bd
	v_fmamk_f32 v188, v188, 0x3a000000, v189
	v_mul_f32_e32 v189, 0x4b800000, v188
	v_cmp_gt_f32_e32 vcc, 0x800000, v188
	s_nop 1
	v_cndmask_b32_e32 v188, v188, v189, vcc
	v_rsq_f32_e32 v188, v188
	s_nop 0
	v_mul_f32_e32 v189, 0x45800000, v188
	v_cndmask_b32_e32 v188, v188, v189, vcc
	v_add_f32_e32 v196, v196, v197
	v_add_f32_e32 v198, v198, v199
	v_add_f32_e32 v200, v200, v201
	v_add_f32_e32 v202, v202, v203
	v_add_f32_e32 v196, v196, v198
	v_add_f32_e32 v200, v200, v202
	v_add_f32_e32 v196, v196, v200
	v_mov_b32_e32 v197, 0x358637bd
	v_fmamk_f32 v196, v196, 0x3a000000, v197
	v_mul_f32_e32 v197, 0x4b800000, v196
	v_cmp_gt_f32_e32 vcc, 0x800000, v196
	s_nop 1
	v_cndmask_b32_e32 v196, v196, v197, vcc
	v_rsq_f32_e32 v196, v196
	s_nop 0
	v_mul_f32_e32 v197, 0x45800000, v196
	v_cndmask_b32_e32 v196, v196, v197, vcc
	s_mov_b64 s[80:81], s[78:79]
	s_mov_b64 s[78:79], s[38:39]
	s_mov_b64 s[38:39], s[22:23]
	s_mov_b32 s22, s49
	s_mov_b32 s49, s47
	s_mov_b32 s47, s84
	s_mov_b32 s84, s48
	s_mov_b32 s48, s61
	s_mov_b32 s61, 0x800000
	s_nop 1
	v_mov_b32_e32 v128, v204
	v_pk_mul_f32 v[136:137], v[126:127], v[128:129] op_sel_hi:[1,0]
	v_pk_mul_f32 v[138:139], v[124:125], v[128:129] op_sel_hi:[1,0]
	v_pk_mul_f32 v[132:133], v[122:123], v[128:129] op_sel_hi:[1,0]
	v_pk_mul_f32 v[134:135], v[120:121], v[128:129] op_sel_hi:[1,0]
	s_and_b64 vcc, exec, s[2:3]
	s_cbranch_vccz .LBB0_303
	v_mul_f32_e32 v129, 0xbfb8aa3b, v138
	v_exp_f32_e32 v129, v129
	s_nop 0
	v_add_f32_e32 v129, 1.0, v129
	v_rcp_f32_e32 v130, v129
	v_mul_f32_e32 v129, 0xbfb8aa3b, v134
	v_exp_f32_e32 v129, v129
	s_nop 0
	v_add_f32_e32 v129, 1.0, v129
	v_rcp_f32_e32 v140, v129
	v_mul_f32_e32 v129, 0xbfb8aa3b, v139
	v_exp_f32_e32 v129, v129
	s_nop 0
	v_add_f32_e32 v129, 1.0, v129
	v_rcp_f32_e32 v131, v129
	v_mul_f32_e32 v129, 0xbfb8aa3b, v135
	v_exp_f32_e32 v129, v129
	v_pk_mul_f32 v[138:139], v[138:139], v[130:131]
	v_add_f32_e32 v129, 1.0, v129
	v_rcp_f32_e32 v141, v129
	v_mul_f32_e32 v129, 0xbfb8aa3b, v136
	v_exp_f32_e32 v129, v129
	v_pk_mul_f32 v[134:135], v[134:135], v[140:141]
	v_add_f32_e32 v129, 1.0, v129
	v_rcp_f32_e32 v142, v129
	v_mul_f32_e32 v129, 0xbfb8aa3b, v132
	v_exp_f32_e32 v129, v129
	s_nop 0
	v_add_f32_e32 v129, 1.0, v129
	v_rcp_f32_e32 v144, v129
	v_mul_f32_e32 v129, 0xbfb8aa3b, v137
	v_exp_f32_e32 v129, v129
	s_nop 0
	v_add_f32_e32 v129, 1.0, v129
	v_rcp_f32_e32 v143, v129
	v_mul_f32_e32 v129, 0xbfb8aa3b, v133
	v_exp_f32_e32 v129, v129
	v_pk_mul_f32 v[136:137], v[136:137], v[142:143]
	v_add_f32_e32 v129, 1.0, v129
	v_rcp_f32_e32 v145, v129
	s_nop 0
	v_pk_mul_f32 v[132:133], v[132:133], v[144:145]

.LBB0_309:
	v_cvt_pk_bf16_f32 v136, v136, v137
	v_cvt_pk_bf16_f32 v137, v132, v133
	v_cvt_pk_bf16_f32 v138, v128, v129
	v_lshl_add_u64 v[128:129], v[130:131], 1, s[90:91]
	v_or_b32_e32 v130, 16, v224
	v_ashrrev_i32_e32 v131, 31, v130
	v_cvt_pk_bf16_f32 v139, v134, v135
	global_store_dwordx4 v[128:129], v[136:139], off
	s_and_b64 vcc, exec, s[10:11]
	s_nop 1
	v_mov_b32_e32 v132, v205
	v_pk_mul_f32 v[138:139], v[118:119], v[132:133] op_sel_hi:[1,0]
	v_pk_mul_f32 v[140:141], v[116:117], v[132:133] op_sel_hi:[1,0]
	v_pk_mul_f32 v[134:135], v[114:115], v[132:133] op_sel_hi:[1,0]
	v_pk_mul_f32 v[136:137], v[112:113], v[132:133] op_sel_hi:[1,0]
	s_cbranch_vccnz .LBB0_311
	v_mul_f32_e32 v133, 0xbfb8aa3b, v137
	v_exp_f32_e32 v133, v133
	v_mul_f32_e32 v129, 0xbfb8aa3b, v136
	v_exp_f32_e32 v129, v129
	v_mul_f32_e32 v128, 0xbfb8aa3b, v140
	v_add_f32_e32 v133, 1.0, v133
	v_rcp_f32_e32 v145, v133
	v_mul_f32_e32 v133, 0xbfb8aa3b, v138
	v_add_f32_e32 v129, 1.0, v129
	v_exp_f32_e32 v133, v133
	v_rcp_f32_e32 v144, v129
	v_mul_f32_e32 v129, 0xbfb8aa3b, v141
	v_exp_f32_e32 v128, v128
	v_exp_f32_e32 v129, v129
	v_add_f32_e32 v133, 1.0, v133
	v_rcp_f32_e32 v146, v133
	v_mul_f32_e32 v133, 0xbfb8aa3b, v134
	v_add_f32_e32 v128, 1.0, v128
	v_add_f32_e32 v129, 1.0, v129
	v_exp_f32_e32 v133, v133
	v_rcp_f32_e32 v128, v128
	v_rcp_f32_e32 v129, v129
	v_pk_mul_f32 v[136:137], v[136:137], v[144:145]
	v_add_f32_e32 v133, 1.0, v133
	v_rcp_f32_e32 v148, v133
	v_mul_f32_e32 v133, 0xbfb8aa3b, v139
	v_pk_mul_f32 v[140:141], v[140:141], v[128:129]
	v_mul_f32_e32 v128, 0xbfb8aa3b, v135
	v_exp_f32_e32 v133, v133
	v_exp_f32_e32 v128, v128
	v_add_f32_e32 v133, 1.0, v133
	v_add_f32_e32 v128, 1.0, v128
	v_rcp_f32_e32 v147, v133
	v_rcp_f32_e32 v149, v128
	v_pk_mul_f32 v[138:139], v[138:139], v[146:147]
	v_pk_mul_f32 v[134:135], v[134:135], v[148:149]

.LBB0_315:
	v_cvt_pk_bf16_f32 v130, v138, v139
	v_lshl_add_u64 v[128:129], v[128:129], 1, s[90:91]
	v_cvt_pk_bf16_f32 v131, v134, v135
	v_cvt_pk_bf16_f32 v132, v132, v133
	v_cvt_pk_bf16_f32 v133, v136, v137
	global_store_dwordx4 v[128:129], v[130:133], off
	s_and_b64 vcc, exec, s[10:11]
	s_nop 0
	v_or_b32_e32 v130, 32, v224
	v_ashrrev_i32_e32 v131, 31, v130
	s_nop 1
	v_mov_b32_e32 v132, v206
	v_pk_mul_f32 v[138:139], v[110:111], v[132:133] op_sel_hi:[1,0]
	v_pk_mul_f32 v[140:141], v[108:109], v[132:133] op_sel_hi:[1,0]
	v_pk_mul_f32 v[134:135], v[102:103], v[132:133] op_sel_hi:[1,0]
	v_pk_mul_f32 v[136:137], v[100:101], v[132:133] op_sel_hi:[1,0]
	s_cbranch_vccnz .LBB0_317
	v_mul_f32_e32 v133, 0xbfb8aa3b, v137
	v_exp_f32_e32 v133, v133
	v_mul_f32_e32 v129, 0xbfb8aa3b, v136
	v_exp_f32_e32 v129, v129
	v_mul_f32_e32 v128, 0xbfb8aa3b, v140
	v_add_f32_e32 v133, 1.0, v133
	v_rcp_f32_e32 v145, v133
	v_mul_f32_e32 v133, 0xbfb8aa3b, v138
	v_add_f32_e32 v129, 1.0, v129
	v_exp_f32_e32 v133, v133
	v_rcp_f32_e32 v144, v129
	v_mul_f32_e32 v129, 0xbfb8aa3b, v141
	v_exp_f32_e32 v128, v128
	v_exp_f32_e32 v129, v129
	v_add_f32_e32 v133, 1.0, v133
	v_rcp_f32_e32 v146, v133
	v_mul_f32_e32 v133, 0xbfb8aa3b, v134
	v_add_f32_e32 v128, 1.0, v128
	v_add_f32_e32 v129, 1.0, v129
	v_exp_f32_e32 v133, v133
	v_rcp_f32_e32 v128, v128
	v_rcp_f32_e32 v129, v129
	v_pk_mul_f32 v[136:137], v[136:137], v[144:145]
	v_add_f32_e32 v133, 1.0, v133
	v_rcp_f32_e32 v148, v133
	v_mul_f32_e32 v133, 0xbfb8aa3b, v139
	v_pk_mul_f32 v[140:141], v[140:141], v[128:129]
	v_mul_f32_e32 v128, 0xbfb8aa3b, v135
	v_exp_f32_e32 v133, v133
	v_exp_f32_e32 v128, v128
	v_add_f32_e32 v133, 1.0, v133
	v_add_f32_e32 v128, 1.0, v128
	v_rcp_f32_e32 v147, v133
	v_rcp_f32_e32 v149, v128
	v_pk_mul_f32 v[138:139], v[138:139], v[146:147]
	v_pk_mul_f32 v[134:135], v[134:135], v[148:149]

.LBB0_321:
	v_cvt_pk_bf16_f32 v130, v138, v139
	v_lshl_add_u64 v[128:129], v[128:129], 1, s[90:91]
	v_cvt_pk_bf16_f32 v131, v134, v135
	v_cvt_pk_bf16_f32 v132, v132, v133
	v_cvt_pk_bf16_f32 v133, v136, v137
	global_store_dwordx4 v[128:129], v[130:133], off
	s_and_b64 vcc, exec, s[10:11]
	s_nop 0
	v_or_b32_e32 v130, 48, v224
	v_ashrrev_i32_e32 v131, 31, v130
	s_nop 1
	v_mov_b32_e32 v132, v207
	v_pk_mul_f32 v[138:139], v[94:95], v[132:133] op_sel_hi:[1,0]
	v_pk_mul_f32 v[140:141], v[92:93], v[132:133] op_sel_hi:[1,0]
	v_pk_mul_f32 v[134:135], v[86:87], v[132:133] op_sel_hi:[1,0]
	v_pk_mul_f32 v[136:137], v[84:85], v[132:133] op_sel_hi:[1,0]
	s_cbranch_vccnz .LBB0_323
	v_mul_f32_e32 v133, 0xbfb8aa3b, v137
	v_exp_f32_e32 v133, v133
	v_mul_f32_e32 v129, 0xbfb8aa3b, v136
	v_exp_f32_e32 v129, v129
	v_mul_f32_e32 v128, 0xbfb8aa3b, v140
	v_add_f32_e32 v133, 1.0, v133
	v_rcp_f32_e32 v145, v133
	v_mul_f32_e32 v133, 0xbfb8aa3b, v138
	v_add_f32_e32 v129, 1.0, v129
	v_exp_f32_e32 v133, v133
	v_rcp_f32_e32 v144, v129
	v_mul_f32_e32 v129, 0xbfb8aa3b, v141
	v_exp_f32_e32 v128, v128
	v_exp_f32_e32 v129, v129
	v_add_f32_e32 v133, 1.0, v133
	v_rcp_f32_e32 v146, v133
	v_mul_f32_e32 v133, 0xbfb8aa3b, v134
	v_add_f32_e32 v128, 1.0, v128
	v_add_f32_e32 v129, 1.0, v129
	v_exp_f32_e32 v133, v133
	v_rcp_f32_e32 v128, v128
	v_rcp_f32_e32 v129, v129
	v_pk_mul_f32 v[136:137], v[136:137], v[144:145]
	v_add_f32_e32 v133, 1.0, v133
	v_rcp_f32_e32 v148, v133
	v_mul_f32_e32 v133, 0xbfb8aa3b, v139
	v_pk_mul_f32 v[140:141], v[140:141], v[128:129]
	v_mul_f32_e32 v128, 0xbfb8aa3b, v135
	v_exp_f32_e32 v133, v133
	v_exp_f32_e32 v128, v128
	v_add_f32_e32 v133, 1.0, v133
	v_add_f32_e32 v128, 1.0, v128
	v_rcp_f32_e32 v147, v133
	v_rcp_f32_e32 v149, v128
	v_pk_mul_f32 v[138:139], v[138:139], v[146:147]
	v_pk_mul_f32 v[134:135], v[134:135], v[148:149]

.LBB0_329:
	v_cvt_pk_bf16_f32 v130, v138, v139
	v_lshl_add_u64 v[128:129], v[128:129], 1, s[90:91]
	v_cvt_pk_bf16_f32 v131, v134, v135
	v_cvt_pk_bf16_f32 v132, v132, v133
	v_cvt_pk_bf16_f32 v133, v136, v137
	global_store_dwordx4 v[128:129], v[130:133], off
	s_and_b64 vcc, exec, s[10:11]
	s_nop 0
	v_add_u32_e32 v130, 0x80, v224
	v_ashrrev_i32_e32 v131, 31, v130
	s_nop 1
	v_mov_b32_e32 v132, v172
	v_pk_mul_f32 v[138:139], v[62:63], v[132:133] op_sel_hi:[1,0]
	v_pk_mul_f32 v[140:141], v[60:61], v[132:133] op_sel_hi:[1,0]
	v_pk_mul_f32 v[134:135], v[58:59], v[132:133] op_sel_hi:[1,0]
	v_pk_mul_f32 v[136:137], v[56:57], v[132:133] op_sel_hi:[1,0]
	s_cbranch_vccnz .LBB0_331
	v_mul_f32_e32 v133, 0xbfb8aa3b, v137
	v_exp_f32_e32 v133, v133
	v_mul_f32_e32 v129, 0xbfb8aa3b, v136
	v_exp_f32_e32 v129, v129
	v_mul_f32_e32 v128, 0xbfb8aa3b, v140
	v_add_f32_e32 v133, 1.0, v133
	v_rcp_f32_e32 v145, v133
	v_mul_f32_e32 v133, 0xbfb8aa3b, v138
	v_add_f32_e32 v129, 1.0, v129
	v_exp_f32_e32 v133, v133
	v_rcp_f32_e32 v144, v129
	v_mul_f32_e32 v129, 0xbfb8aa3b, v141
	v_exp_f32_e32 v128, v128
	v_exp_f32_e32 v129, v129
	v_add_f32_e32 v133, 1.0, v133
	v_rcp_f32_e32 v146, v133
	v_mul_f32_e32 v133, 0xbfb8aa3b, v134
	v_add_f32_e32 v128, 1.0, v128
	v_add_f32_e32 v129, 1.0, v129
	v_exp_f32_e32 v133, v133
	v_rcp_f32_e32 v128, v128
	v_rcp_f32_e32 v129, v129
	v_pk_mul_f32 v[136:137], v[136:137], v[144:145]
	v_add_f32_e32 v133, 1.0, v133
	v_rcp_f32_e32 v148, v133
	v_mul_f32_e32 v133, 0xbfb8aa3b, v139
	v_pk_mul_f32 v[140:141], v[140:141], v[128:129]
	v_mul_f32_e32 v128, 0xbfb8aa3b, v135
	v_exp_f32_e32 v133, v133
	v_exp_f32_e32 v128, v128
	v_add_f32_e32 v133, 1.0, v133
	v_add_f32_e32 v128, 1.0, v128
	v_rcp_f32_e32 v147, v133
	v_rcp_f32_e32 v149, v128
	v_pk_mul_f32 v[138:139], v[138:139], v[146:147]
	v_pk_mul_f32 v[134:135], v[134:135], v[148:149]

.LBB0_337:
	v_cvt_pk_bf16_f32 v130, v138, v139
	v_lshl_add_u64 v[128:129], v[128:129], 1, s[90:91]
	v_cvt_pk_bf16_f32 v131, v134, v135
	v_cvt_pk_bf16_f32 v132, v132, v133
	v_cvt_pk_bf16_f32 v133, v136, v137
	global_store_dwordx4 v[128:129], v[130:133], off
	s_and_b64 vcc, exec, s[10:11]
	s_mov_b64 s[22:23], s[38:39]
	v_add_u32_e32 v130, 0x90, v224
	v_ashrrev_i32_e32 v131, 31, v130
	s_nop 1
	v_mov_b32_e32 v132, v180
	v_pk_mul_f32 v[138:139], v[54:55], v[132:133] op_sel_hi:[1,0]
	v_pk_mul_f32 v[140:141], v[52:53], v[132:133] op_sel_hi:[1,0]
	v_pk_mul_f32 v[134:135], v[50:51], v[132:133] op_sel_hi:[1,0]
	v_pk_mul_f32 v[136:137], v[48:49], v[132:133] op_sel_hi:[1,0]
	s_cbranch_vccnz .LBB0_339
	v_mul_f32_e32 v133, 0xbfb8aa3b, v137
	v_exp_f32_e32 v133, v133
	v_mul_f32_e32 v129, 0xbfb8aa3b, v136
	v_exp_f32_e32 v129, v129
	v_mul_f32_e32 v128, 0xbfb8aa3b, v140
	v_add_f32_e32 v133, 1.0, v133
	v_rcp_f32_e32 v145, v133
	v_mul_f32_e32 v133, 0xbfb8aa3b, v138
	v_add_f32_e32 v129, 1.0, v129
	v_exp_f32_e32 v133, v133
	v_rcp_f32_e32 v144, v129
	v_mul_f32_e32 v129, 0xbfb8aa3b, v141
	v_exp_f32_e32 v128, v128
	v_exp_f32_e32 v129, v129
	v_add_f32_e32 v133, 1.0, v133
	v_rcp_f32_e32 v146, v133
	v_mul_f32_e32 v133, 0xbfb8aa3b, v134
	v_add_f32_e32 v128, 1.0, v128
	v_add_f32_e32 v129, 1.0, v129
	v_exp_f32_e32 v133, v133
	v_rcp_f32_e32 v128, v128
	v_rcp_f32_e32 v129, v129
	v_pk_mul_f32 v[136:137], v[136:137], v[144:145]
	v_add_f32_e32 v133, 1.0, v133
	v_rcp_f32_e32 v148, v133
	v_mul_f32_e32 v133, 0xbfb8aa3b, v139
	v_pk_mul_f32 v[140:141], v[140:141], v[128:129]
	v_mul_f32_e32 v128, 0xbfb8aa3b, v135
	v_exp_f32_e32 v133, v133
	v_exp_f32_e32 v128, v128
	v_add_f32_e32 v133, 1.0, v133
	v_add_f32_e32 v128, 1.0, v128
	v_rcp_f32_e32 v147, v133
	v_rcp_f32_e32 v149, v128
	v_pk_mul_f32 v[138:139], v[138:139], v[146:147]
	v_pk_mul_f32 v[134:135], v[134:135], v[148:149]

.LBB0_345:
	v_cvt_pk_bf16_f32 v130, v138, v139
	v_lshl_add_u64 v[128:129], v[128:129], 1, s[90:91]
	v_cvt_pk_bf16_f32 v131, v134, v135
	v_cvt_pk_bf16_f32 v132, v132, v133
	v_cvt_pk_bf16_f32 v133, v136, v137
	global_store_dwordx4 v[128:129], v[130:133], off
	s_and_b64 vcc, exec, s[10:11]
	s_nop 0
	v_add_u32_e32 v130, 0xa0, v224
	v_ashrrev_i32_e32 v131, 31, v130
	s_nop 1
	v_mov_b32_e32 v132, v188
	v_pk_mul_f32 v[138:139], v[46:47], v[132:133] op_sel_hi:[1,0]
	v_pk_mul_f32 v[140:141], v[44:45], v[132:133] op_sel_hi:[1,0]
	v_pk_mul_f32 v[134:135], v[38:39], v[132:133] op_sel_hi:[1,0]
	v_pk_mul_f32 v[136:137], v[36:37], v[132:133] op_sel_hi:[1,0]
	s_cbranch_vccnz .LBB0_347
	v_mul_f32_e32 v133, 0xbfb8aa3b, v137
	v_exp_f32_e32 v133, v133
	v_mul_f32_e32 v129, 0xbfb8aa3b, v136
	v_exp_f32_e32 v129, v129
	v_mul_f32_e32 v128, 0xbfb8aa3b, v140
	v_add_f32_e32 v133, 1.0, v133
	v_rcp_f32_e32 v145, v133
	v_mul_f32_e32 v133, 0xbfb8aa3b, v138
	v_add_f32_e32 v129, 1.0, v129
	v_exp_f32_e32 v133, v133
	v_rcp_f32_e32 v144, v129
	v_mul_f32_e32 v129, 0xbfb8aa3b, v141
	v_exp_f32_e32 v128, v128
	v_exp_f32_e32 v129, v129
	v_add_f32_e32 v133, 1.0, v133
	v_rcp_f32_e32 v146, v133
	v_mul_f32_e32 v133, 0xbfb8aa3b, v134
	v_add_f32_e32 v128, 1.0, v128
	v_add_f32_e32 v129, 1.0, v129
	v_exp_f32_e32 v133, v133
	v_rcp_f32_e32 v128, v128
	v_rcp_f32_e32 v129, v129
	v_pk_mul_f32 v[136:137], v[136:137], v[144:145]
	v_add_f32_e32 v133, 1.0, v133
	v_rcp_f32_e32 v148, v133
	v_mul_f32_e32 v133, 0xbfb8aa3b, v139
	v_pk_mul_f32 v[140:141], v[140:141], v[128:129]
	v_mul_f32_e32 v128, 0xbfb8aa3b, v135
	v_exp_f32_e32 v133, v133
	v_exp_f32_e32 v128, v128
	v_add_f32_e32 v133, 1.0, v133
	v_add_f32_e32 v128, 1.0, v128
	v_rcp_f32_e32 v147, v133
	v_rcp_f32_e32 v149, v128
	v_pk_mul_f32 v[138:139], v[138:139], v[146:147]
	v_pk_mul_f32 v[134:135], v[134:135], v[148:149]

.LBB0_351:
	v_cvt_pk_bf16_f32 v130, v138, v139
	v_lshl_add_u64 v[128:129], v[128:129], 1, s[90:91]
	v_cvt_pk_bf16_f32 v131, v134, v135
	v_cvt_pk_bf16_f32 v132, v132, v133
	v_cvt_pk_bf16_f32 v133, v136, v137
	global_store_dwordx4 v[128:129], v[130:133], off
	s_and_b64 vcc, exec, s[10:11]
	s_nop 0
	v_add_u32_e32 v130, 0xb0, v224
	v_ashrrev_i32_e32 v131, 31, v130
	s_nop 1
	v_mov_b32_e32 v132, v196
	v_pk_mul_f32 v[138:139], v[30:31], v[132:133] op_sel_hi:[1,0]
	v_pk_mul_f32 v[140:141], v[28:29], v[132:133] op_sel_hi:[1,0]
	v_pk_mul_f32 v[134:135], v[22:23], v[132:133] op_sel_hi:[1,0]
	v_pk_mul_f32 v[136:137], v[20:21], v[132:133] op_sel_hi:[1,0]
	s_cbranch_vccnz .LBB0_353
	v_mul_f32_e32 v133, 0xbfb8aa3b, v137
	v_exp_f32_e32 v133, v133
	v_mul_f32_e32 v129, 0xbfb8aa3b, v136
	v_exp_f32_e32 v129, v129
	v_mul_f32_e32 v128, 0xbfb8aa3b, v140
	v_add_f32_e32 v133, 1.0, v133
	v_rcp_f32_e32 v145, v133
	v_mul_f32_e32 v133, 0xbfb8aa3b, v138
	v_add_f32_e32 v129, 1.0, v129
	v_exp_f32_e32 v133, v133
	v_rcp_f32_e32 v144, v129
	v_mul_f32_e32 v129, 0xbfb8aa3b, v141
	v_exp_f32_e32 v128, v128
	v_exp_f32_e32 v129, v129
	v_add_f32_e32 v133, 1.0, v133
	v_rcp_f32_e32 v146, v133
	v_mul_f32_e32 v133, 0xbfb8aa3b, v134
	v_add_f32_e32 v128, 1.0, v128
	v_add_f32_e32 v129, 1.0, v129
	v_exp_f32_e32 v133, v133
	v_rcp_f32_e32 v128, v128
	v_rcp_f32_e32 v129, v129
	v_pk_mul_f32 v[136:137], v[136:137], v[144:145]
	v_add_f32_e32 v133, 1.0, v133
	v_rcp_f32_e32 v148, v133
	v_mul_f32_e32 v133, 0xbfb8aa3b, v139
	v_pk_mul_f32 v[140:141], v[140:141], v[128:129]
	v_mul_f32_e32 v128, 0xbfb8aa3b, v135
	v_exp_f32_e32 v133, v133
	v_exp_f32_e32 v128, v128
	v_add_f32_e32 v133, 1.0, v133
	v_add_f32_e32 v128, 1.0, v128
	v_rcp_f32_e32 v147, v133
	v_rcp_f32_e32 v149, v128
	v_pk_mul_f32 v[138:139], v[138:139], v[146:147]
	v_pk_mul_f32 v[134:135], v[134:135], v[148:149]

.LBB0_361:
	s_or_b64 exec, exec, s[2:3]
	v_mov_b32_e32 v155, v154
	s_waitcnt lgkmcnt(0)
	v_mov_b32_e32 v132, v154
	v_mov_b32_e32 v133, v154
	v_pk_mul_f32 v[134:135], v[106:107], v[132:133]
	v_pk_mul_f32 v[136:137], v[104:105], v[154:155]
	v_pk_mul_f32 v[138:139], v[96:97], v[154:155]
	v_mul_f32_e32 v131, v137, v137
	v_mul_f32_e32 v135, v135, v135
	v_pk_mul_f32 v[132:133], v[98:99], v[132:133]
	v_fmac_f32_e32 v131, v136, v136
	v_fmac_f32_e32 v135, v134, v134
	v_mul_f32_e32 v134, v139, v139
	v_add_f32_e32 v131, v131, v135
	v_fmac_f32_e32 v134, v138, v138
	v_mul_f32_e32 v133, v133, v133
	v_add_f32_e32 v131, v134, v131
	v_fmac_f32_e32 v133, v132, v132
	v_add_f32_e32 v131, v133, v131
	v_mov_b32_e32 v132, v131
	s_nop 1
	v_permlane16_swap_b32_e32 v131, v132
	v_add_f32_e32 v131, v131, v132
	v_mov_b32_e32 v132, v131
	s_nop 1
	v_permlane32_swap_b32_e32 v131, v132
	s_and_saveexec_b64 s[2:3], s[8:9]
	s_cbranch_execz .LBB0_363
	s_waitcnt lgkmcnt(0)
	v_add_f32_e32 v131, v131, v132
	ds_write_b32 v130, v131 offset:16
.LBB0_363:
	s_or_b64 exec, exec, s[2:3]
	s_waitcnt lgkmcnt(0)
	v_or_b32_e32 v132, 16, v224
	v_ashrrev_i32_e32 v133, 31, v132
	v_lshlrev_b64 v[132:133], 5, v[132:133]
	v_lshl_add_u64 v[136:137], s[44:45], 0, v[132:133]
	global_load_dwordx4 v[132:135], v[136:137], off
	s_nop 0
	global_load_dwordx4 v[136:139], v[136:137], off offset:16
	s_waitcnt vmcnt(1)
	v_mov_b32_e32 v140, v132
	s_waitcnt vmcnt(0)
	v_mov_b32_e32 v141, v136
	v_mov_b32_e32 v136, v133
	v_mov_b32_e32 v132, v134
	v_mov_b32_e32 v133, v138
	v_mov_b32_e32 v138, v135
	v_pk_add_f32 v[134:135], v[140:141], v[136:137]
	v_pk_add_f32 v[132:133], v[132:133], v[138:139]
	s_nop 0
	v_pk_add_f32 v[132:133], v[134:135], v[132:133]
	s_nop 0
	v_add_f32_e32 v131, v132, v133
	v_mov_b32_e32 v132, 0x358637bd
	v_fmamk_f32 v131, v131, 0x3a000000, v132
	v_mul_f32_e32 v132, 0x4b800000, v131
	v_cmp_gt_f32_e32 vcc, s92, v131
	s_nop 1
	v_cndmask_b32_e32 v131, v131, v132, vcc
	v_rsq_f32_e32 v131, v131
	s_nop 0
	v_mul_f32_e32 v132, 0x45800000, v131
	v_cndmask_b32_e32 v152, v131, v132, vcc
	v_pk_mul_f32 v[132:133], v[118:119], v[152:153] op_sel_hi:[1,0]
	v_pk_mul_f32 v[134:135], v[116:117], v[152:153] op_sel_hi:[1,0]
	v_pk_mul_f32 v[138:139], v[112:113], v[152:153] op_sel_hi:[1,0]
	v_mul_f32_e32 v131, v135, v135
	v_mul_f32_e32 v133, v133, v133
	v_pk_mul_f32 v[136:137], v[114:115], v[152:153] op_sel_hi:[1,0]
	v_mul_f32_e32 v135, v139, v139
	v_fmac_f32_e32 v131, v134, v134
	v_fmac_f32_e32 v133, v132, v132
	v_mul_f32_e32 v137, v137, v137
	v_fmac_f32_e32 v135, v138, v138
	v_add_f32_e32 v131, v131, v133
	v_add_f32_e32 v131, v135, v131
	v_fmac_f32_e32 v137, v136, v136
	v_add_f32_e32 v131, v137, v131
	v_mov_b32_e32 v132, v131
	s_nop 1
	v_permlane16_swap_b32_e32 v131, v132
	v_add_f32_e32 v131, v131, v132
	v_mov_b32_e32 v132, v131
	s_nop 1
	v_permlane32_swap_b32_e32 v131, v132
	s_and_saveexec_b64 s[2:3], s[8:9]
	s_cbranch_execz .LBB0_365
	s_waitcnt lgkmcnt(0)
	v_add_f32_e32 v131, v131, v132
	ds_write_b32 v130, v131 offset:512
.LBB0_365:
	s_or_b64 exec, exec, s[2:3]
	v_mov_b32_e32 v153, v152
	s_waitcnt lgkmcnt(0)
	v_mov_b32_e32 v132, v152
	v_mov_b32_e32 v133, v152
	v_pk_mul_f32 v[134:135], v[90:91], v[132:133]
	v_pk_mul_f32 v[136:137], v[88:89], v[152:153]
	v_pk_mul_f32 v[138:139], v[80:81], v[152:153]
	v_mul_f32_e32 v131, v137, v137
	v_mul_f32_e32 v135, v135, v135
	v_pk_mul_f32 v[132:133], v[82:83], v[132:133]
	v_fmac_f32_e32 v131, v136, v136
	v_fmac_f32_e32 v135, v134, v134
	v_mul_f32_e32 v134, v139, v139
	v_add_f32_e32 v131, v131, v135
	v_fmac_f32_e32 v134, v138, v138
	v_mul_f32_e32 v133, v133, v133
	v_add_f32_e32 v131, v134, v131
	v_fmac_f32_e32 v133, v132, v132
	v_add_f32_e32 v131, v133, v131
	v_mov_b32_e32 v132, v131
	s_nop 1
	v_permlane16_swap_b32_e32 v131, v132
	v_add_f32_e32 v131, v131, v132
	v_mov_b32_e32 v132, v131
	s_nop 1
	v_permlane32_swap_b32_e32 v131, v132
	s_and_saveexec_b64 s[2:3], s[8:9]
	s_cbranch_execz .LBB0_367
	s_waitcnt lgkmcnt(0)
	v_add_f32_e32 v131, v131, v132
	ds_write_b32 v130, v131 offset:528
.LBB0_367:
	s_or_b64 exec, exec, s[2:3]
	s_waitcnt lgkmcnt(0)
	v_or_b32_e32 v132, 32, v224
	v_ashrrev_i32_e32 v133, 31, v132
	v_lshlrev_b64 v[132:133], 5, v[132:133]
	v_lshl_add_u64 v[136:137], s[44:45], 0, v[132:133]
	global_load_dwordx4 v[132:135], v[136:137], off
	s_nop 0
	global_load_dwordx4 v[136:139], v[136:137], off offset:16
	s_waitcnt vmcnt(1)
	v_mov_b32_e32 v140, v132
	s_waitcnt vmcnt(0)
	v_mov_b32_e32 v141, v136
	v_mov_b32_e32 v136, v133
	v_mov_b32_e32 v132, v134
	v_mov_b32_e32 v133, v138
	v_mov_b32_e32 v138, v135
	v_pk_add_f32 v[134:135], v[140:141], v[136:137]
	v_pk_add_f32 v[132:133], v[132:133], v[138:139]
	s_nop 0
	v_pk_add_f32 v[132:133], v[134:135], v[132:133]
	s_nop 0
	v_add_f32_e32 v131, v132, v133
	v_mov_b32_e32 v132, 0x358637bd
	v_fmamk_f32 v131, v131, 0x3a000000, v132
	v_mul_f32_e32 v132, 0x4b800000, v131
	v_cmp_gt_f32_e32 vcc, s92, v131
	s_nop 1
	v_cndmask_b32_e32 v131, v131, v132, vcc
	v_rsq_f32_e32 v131, v131
	s_nop 0
	v_mul_f32_e32 v132, 0x45800000, v131
	v_cndmask_b32_e32 v150, v131, v132, vcc
	v_pk_mul_f32 v[132:133], v[110:111], v[150:151] op_sel_hi:[1,0]
	v_pk_mul_f32 v[134:135], v[108:109], v[150:151] op_sel_hi:[1,0]
	v_pk_mul_f32 v[138:139], v[100:101], v[150:151] op_sel_hi:[1,0]
	v_mul_f32_e32 v131, v135, v135
	v_mul_f32_e32 v133, v133, v133
	v_pk_mul_f32 v[136:137], v[102:103], v[150:151] op_sel_hi:[1,0]
	v_mul_f32_e32 v135, v139, v139
	v_fmac_f32_e32 v131, v134, v134
	v_fmac_f32_e32 v133, v132, v132
	v_mul_f32_e32 v137, v137, v137
	v_fmac_f32_e32 v135, v138, v138
	v_add_f32_e32 v131, v131, v133
	v_add_f32_e32 v131, v135, v131
	v_fmac_f32_e32 v137, v136, v136
	v_add_f32_e32 v131, v137, v131
	v_mov_b32_e32 v132, v131
	s_nop 1
	v_permlane16_swap_b32_e32 v131, v132
	v_add_f32_e32 v131, v131, v132
	v_mov_b32_e32 v132, v131
	s_nop 1
	v_permlane32_swap_b32_e32 v131, v132
	s_and_saveexec_b64 s[2:3], s[8:9]
	s_cbranch_execz .LBB0_369
	s_waitcnt lgkmcnt(0)
	v_add_f32_e32 v131, v131, v132
	ds_write_b32 v130, v131 offset:1024
.LBB0_369:
	s_or_b64 exec, exec, s[2:3]
	v_mov_b32_e32 v151, v150
	s_waitcnt lgkmcnt(0)
	v_mov_b32_e32 v132, v150
	v_mov_b32_e32 v133, v150
	v_pk_mul_f32 v[134:135], v[78:79], v[132:133]
	v_pk_mul_f32 v[136:137], v[76:77], v[150:151]
	v_pk_mul_f32 v[138:139], v[72:73], v[150:151]
	v_mul_f32_e32 v131, v137, v137
	v_mul_f32_e32 v135, v135, v135
	v_pk_mul_f32 v[132:133], v[74:75], v[132:133]
	v_fmac_f32_e32 v131, v136, v136
	v_fmac_f32_e32 v135, v134, v134
	v_mul_f32_e32 v134, v139, v139
	v_add_f32_e32 v131, v131, v135
	v_fmac_f32_e32 v134, v138, v138
	v_mul_f32_e32 v133, v133, v133
	v_add_f32_e32 v131, v134, v131
	v_fmac_f32_e32 v133, v132, v132
	v_add_f32_e32 v131, v133, v131
	v_mov_b32_e32 v132, v131
	s_nop 1
	v_permlane16_swap_b32_e32 v131, v132
	v_add_f32_e32 v131, v131, v132
	v_mov_b32_e32 v132, v131
	s_nop 1
	v_permlane32_swap_b32_e32 v131, v132
	s_and_saveexec_b64 s[2:3], s[8:9]
	s_cbranch_execz .LBB0_371
	s_waitcnt lgkmcnt(0)
	v_add_f32_e32 v131, v131, v132
	ds_write_b32 v130, v131 offset:1040
.LBB0_371:
	s_or_b64 exec, exec, s[2:3]
	s_waitcnt lgkmcnt(0)
	v_or_b32_e32 v132, 48, v224
	v_ashrrev_i32_e32 v133, 31, v132
	v_lshlrev_b64 v[132:133], 5, v[132:133]
	v_lshl_add_u64 v[136:137], s[44:45], 0, v[132:133]
	global_load_dwordx4 v[132:135], v[136:137], off
	s_nop 0
	global_load_dwordx4 v[136:139], v[136:137], off offset:16
	s_waitcnt vmcnt(1)
	v_mov_b32_e32 v140, v132
	s_waitcnt vmcnt(0)
	v_mov_b32_e32 v141, v136
	v_mov_b32_e32 v136, v133
	v_mov_b32_e32 v132, v134
	v_mov_b32_e32 v133, v138
	v_mov_b32_e32 v138, v135
	v_pk_add_f32 v[134:135], v[140:141], v[136:137]
	v_pk_add_f32 v[132:133], v[132:133], v[138:139]
	s_nop 0
	v_pk_add_f32 v[132:133], v[134:135], v[132:133]
	s_nop 0
	v_add_f32_e32 v131, v132, v133
	v_mov_b32_e32 v132, 0x358637bd
	v_fmamk_f32 v131, v131, 0x3a000000, v132
	v_mul_f32_e32 v132, 0x4b800000, v131
	v_cmp_gt_f32_e32 vcc, s92, v131
	s_nop 1
	v_cndmask_b32_e32 v131, v131, v132, vcc
	v_rsq_f32_e32 v131, v131
	s_nop 0
	v_mul_f32_e32 v132, 0x45800000, v131
	v_cndmask_b32_e32 v146, v131, v132, vcc
	v_pk_mul_f32 v[132:133], v[94:95], v[146:147] op_sel_hi:[1,0]
	v_pk_mul_f32 v[134:135], v[92:93], v[146:147] op_sel_hi:[1,0]
	v_pk_mul_f32 v[138:139], v[84:85], v[146:147] op_sel_hi:[1,0]
	v_mul_f32_e32 v131, v135, v135
	v_mul_f32_e32 v133, v133, v133
	v_pk_mul_f32 v[136:137], v[86:87], v[146:147] op_sel_hi:[1,0]
	v_mul_f32_e32 v135, v139, v139
	v_fmac_f32_e32 v131, v134, v134
	v_fmac_f32_e32 v133, v132, v132
	v_mul_f32_e32 v137, v137, v137
	v_fmac_f32_e32 v135, v138, v138
	v_add_f32_e32 v131, v131, v133
	v_add_f32_e32 v131, v135, v131
	v_fmac_f32_e32 v137, v136, v136
	v_add_f32_e32 v131, v137, v131
	v_mov_b32_e32 v132, v131
	s_nop 1
	v_permlane16_swap_b32_e32 v131, v132
	v_add_f32_e32 v131, v131, v132
	v_mov_b32_e32 v132, v131
	s_nop 1
	v_permlane32_swap_b32_e32 v131, v132
	s_and_saveexec_b64 s[2:3], s[8:9]
	s_cbranch_execz .LBB0_373
	s_waitcnt lgkmcnt(0)
	v_add_f32_e32 v131, v131, v132
	ds_write_b32 v130, v131 offset:1536
.LBB0_373:
	s_or_b64 exec, exec, s[2:3]
	v_mov_b32_e32 v147, v146
	s_waitcnt lgkmcnt(0)
	v_mov_b32_e32 v132, v146
	v_mov_b32_e32 v133, v146
	v_pk_mul_f32 v[134:135], v[70:71], v[132:133]
	v_pk_mul_f32 v[136:137], v[68:69], v[146:147]
	v_pk_mul_f32 v[138:139], v[64:65], v[146:147]
	v_mul_f32_e32 v131, v137, v137
	v_mul_f32_e32 v135, v135, v135
	v_pk_mul_f32 v[132:133], v[66:67], v[132:133]
	v_fmac_f32_e32 v131, v136, v136
	v_fmac_f32_e32 v135, v134, v134
	v_mul_f32_e32 v134, v139, v139
	v_add_f32_e32 v131, v131, v135
	v_fmac_f32_e32 v134, v138, v138
	v_mul_f32_e32 v133, v133, v133
	v_add_f32_e32 v131, v134, v131
	v_fmac_f32_e32 v133, v132, v132
	v_add_f32_e32 v131, v133, v131
	v_mov_b32_e32 v132, v131
	s_nop 1
	v_permlane16_swap_b32_e32 v131, v132
	v_add_f32_e32 v131, v131, v132
	v_mov_b32_e32 v132, v131
	s_nop 1
	v_permlane32_swap_b32_e32 v131, v132
	s_and_saveexec_b64 s[2:3], s[8:9]
	s_cbranch_execz .LBB0_375
	s_waitcnt lgkmcnt(0)
	v_add_f32_e32 v131, v131, v132
	ds_write_b32 v130, v131 offset:1552
.LBB0_375:
	s_or_b64 exec, exec, s[2:3]
	v_add_u32_e32 v148, 0x80, v224
	v_ashrrev_i32_e32 v149, 31, v148
	s_waitcnt lgkmcnt(0)
	v_lshlrev_b64 v[132:133], 5, v[148:149]
	v_lshl_add_u64 v[136:137], s[44:45], 0, v[132:133]
	global_load_dwordx4 v[132:135], v[136:137], off
	s_nop 0
	global_load_dwordx4 v[136:139], v[136:137], off offset:16
	s_waitcnt vmcnt(1)
	v_mov_b32_e32 v140, v132
	s_waitcnt vmcnt(0)
	v_mov_b32_e32 v141, v136
	v_mov_b32_e32 v136, v133
	v_mov_b32_e32 v132, v134
	v_mov_b32_e32 v133, v138
	v_mov_b32_e32 v138, v135
	v_pk_add_f32 v[134:135], v[140:141], v[136:137]
	v_pk_add_f32 v[132:133], v[132:133], v[138:139]
	s_nop 0
	v_pk_add_f32 v[132:133], v[134:135], v[132:133]
	s_nop 0
	v_add_f32_e32 v131, v132, v133
	v_mov_b32_e32 v132, 0x358637bd
	v_fmamk_f32 v131, v131, 0x3a000000, v132
	v_mul_f32_e32 v132, 0x4b800000, v131
	v_cmp_gt_f32_e32 vcc, s92, v131
	s_nop 1
	v_cndmask_b32_e32 v131, v131, v132, vcc
	v_rsq_f32_e32 v131, v131
	s_nop 0
	v_mul_f32_e32 v132, 0x45800000, v131
	v_cndmask_b32_e32 v144, v131, v132, vcc
	v_pk_mul_f32 v[132:133], v[62:63], v[144:145] op_sel_hi:[1,0]
	v_pk_mul_f32 v[134:135], v[60:61], v[144:145] op_sel_hi:[1,0]
	v_pk_mul_f32 v[138:139], v[56:57], v[144:145] op_sel_hi:[1,0]
	v_mul_f32_e32 v131, v135, v135
	v_mul_f32_e32 v133, v133, v133
	v_pk_mul_f32 v[136:137], v[58:59], v[144:145] op_sel_hi:[1,0]
	v_mul_f32_e32 v135, v139, v139
	v_fmac_f32_e32 v131, v134, v134
	v_fmac_f32_e32 v133, v132, v132
	v_mul_f32_e32 v137, v137, v137
	v_fmac_f32_e32 v135, v138, v138
	v_add_f32_e32 v131, v131, v133
	v_add_f32_e32 v131, v135, v131
	v_fmac_f32_e32 v137, v136, v136
	v_add_f32_e32 v131, v137, v131
	v_mov_b32_e32 v132, v131
	s_nop 1
	v_permlane16_swap_b32_e32 v131, v132
	v_add_f32_e32 v131, v131, v132
	v_mov_b32_e32 v132, v131
	s_nop 1
	v_permlane32_swap_b32_e32 v131, v132
	s_and_saveexec_b64 s[2:3], s[8:9]
	s_cbranch_execz .LBB0_377
	s_waitcnt lgkmcnt(0)
	v_add_f32_e32 v131, v131, v132
	ds_write_b32 v130, v131 offset:4096
.LBB0_377:
	s_or_b64 exec, exec, s[2:3]
	v_mov_b32_e32 v145, v144
	s_waitcnt lgkmcnt(0)
	v_mov_b32_e32 v132, v144
	v_mov_b32_e32 v133, v144
	v_pk_mul_f32 v[134:135], v[42:43], v[132:133]
	v_pk_mul_f32 v[136:137], v[40:41], v[144:145]
	v_pk_mul_f32 v[138:139], v[32:33], v[144:145]
	v_mul_f32_e32 v131, v137, v137
	v_mul_f32_e32 v135, v135, v135
	v_pk_mul_f32 v[132:133], v[34:35], v[132:133]
	v_fmac_f32_e32 v131, v136, v136
	v_fmac_f32_e32 v135, v134, v134
	v_mul_f32_e32 v134, v139, v139
	v_add_f32_e32 v131, v131, v135
	v_fmac_f32_e32 v134, v138, v138
	v_mul_f32_e32 v133, v133, v133
	v_add_f32_e32 v131, v134, v131
	v_fmac_f32_e32 v133, v132, v132
	v_add_f32_e32 v131, v133, v131
	v_mov_b32_e32 v132, v131
	s_nop 1
	v_permlane16_swap_b32_e32 v131, v132
	v_add_f32_e32 v131, v131, v132
	v_mov_b32_e32 v132, v131
	s_nop 1
	v_permlane32_swap_b32_e32 v131, v132
	s_and_saveexec_b64 s[2:3], s[8:9]
	s_cbranch_execz .LBB0_379
	s_waitcnt lgkmcnt(0)
	v_add_f32_e32 v131, v131, v132
	ds_write_b32 v130, v131 offset:4112
.LBB0_379:
	s_or_b64 exec, exec, s[2:3]
	s_waitcnt lgkmcnt(0)
	v_lshlrev_b64 v[132:133], 5, v[224:225]
	v_lshl_add_u64 v[132:133], s[44:45], 0, v[132:133]
	s_mov_b64 s[2:3], 0x1200
	v_lshl_add_u64 v[136:137], v[132:133], 0, s[2:3]
	v_add_co_u32_e32 v132, vcc, 0x1000, v132
	s_nop 1
	v_addc_co_u32_e32 v133, vcc, 0, v133, vcc
	global_load_dwordx4 v[132:135], v[132:133], off offset:512
	s_nop 0
	global_load_dwordx4 v[136:139], v[136:137], off offset:16
	s_waitcnt vmcnt(1)
	v_mov_b32_e32 v140, v132
	s_waitcnt vmcnt(0)
	v_mov_b32_e32 v141, v136
	v_mov_b32_e32 v136, v133
	v_mov_b32_e32 v132, v134
	v_mov_b32_e32 v133, v138
	v_mov_b32_e32 v138, v135
	v_pk_add_f32 v[134:135], v[140:141], v[136:137]
	v_pk_add_f32 v[132:133], v[132:133], v[138:139]
	s_nop 0
	v_pk_add_f32 v[132:133], v[134:135], v[132:133]
	s_nop 0
	v_add_f32_e32 v131, v132, v133
	v_mov_b32_e32 v132, 0x358637bd
	v_fmamk_f32 v131, v131, 0x3a000000, v132
	v_mul_f32_e32 v132, 0x4b800000, v131
	v_cmp_gt_f32_e32 vcc, s92, v131
	s_nop 1
	v_cndmask_b32_e32 v131, v131, v132, vcc
	v_rsq_f32_e32 v131, v131
	s_nop 0
	v_mul_f32_e32 v132, 0x45800000, v131
	v_cndmask_b32_e32 v142, v131, v132, vcc
	v_pk_mul_f32 v[132:133], v[54:55], v[142:143] op_sel_hi:[1,0]
	v_pk_mul_f32 v[134:135], v[52:53], v[142:143] op_sel_hi:[1,0]
	v_pk_mul_f32 v[138:139], v[48:49], v[142:143] op_sel_hi:[1,0]
	v_mul_f32_e32 v131, v135, v135
	v_mul_f32_e32 v133, v133, v133
	v_pk_mul_f32 v[136:137], v[50:51], v[142:143] op_sel_hi:[1,0]
	v_mul_f32_e32 v135, v139, v139
	v_fmac_f32_e32 v131, v134, v134
	v_fmac_f32_e32 v133, v132, v132
	v_mul_f32_e32 v137, v137, v137
	v_fmac_f32_e32 v135, v138, v138
	v_add_f32_e32 v131, v131, v133
	v_add_f32_e32 v131, v135, v131
	v_fmac_f32_e32 v137, v136, v136
	v_add_f32_e32 v131, v137, v131
	v_mov_b32_e32 v132, v131
	s_nop 1
	v_permlane16_swap_b32_e32 v131, v132
	v_add_f32_e32 v131, v131, v132
	v_mov_b32_e32 v132, v131
	s_nop 1
	v_permlane32_swap_b32_e32 v131, v132
	s_and_saveexec_b64 s[2:3], s[8:9]
	s_cbranch_execz .LBB0_381
	s_waitcnt lgkmcnt(0)
	v_add_f32_e32 v131, v131, v132
	ds_write_b32 v130, v131 offset:4608
.LBB0_381:
	s_or_b64 exec, exec, s[2:3]
	v_mov_b32_e32 v143, v142
	s_waitcnt lgkmcnt(0)
	v_mov_b32_e32 v132, v142
	v_mov_b32_e32 v133, v142
	v_pk_mul_f32 v[134:135], v[26:27], v[132:133]
	v_pk_mul_f32 v[136:137], v[24:25], v[142:143]
	v_pk_mul_f32 v[138:139], v[16:17], v[142:143]
	v_mul_f32_e32 v131, v137, v137
	v_mul_f32_e32 v135, v135, v135
	v_pk_mul_f32 v[132:133], v[18:19], v[132:133]
	v_fmac_f32_e32 v131, v136, v136
	v_fmac_f32_e32 v135, v134, v134
	v_mul_f32_e32 v134, v139, v139
	v_add_f32_e32 v131, v131, v135
	v_fmac_f32_e32 v134, v138, v138
	v_mul_f32_e32 v133, v133, v133
	v_add_f32_e32 v131, v134, v131
	v_fmac_f32_e32 v133, v132, v132
	v_add_f32_e32 v131, v133, v131
	v_mov_b32_e32 v132, v131
	s_nop 1
	v_permlane16_swap_b32_e32 v131, v132
	v_add_f32_e32 v131, v131, v132
	v_mov_b32_e32 v132, v131
	s_nop 1
	v_permlane32_swap_b32_e32 v131, v132
	s_and_saveexec_b64 s[2:3], s[8:9]
	s_cbranch_execz .LBB0_383
	s_waitcnt lgkmcnt(0)
	v_add_f32_e32 v131, v131, v132
	ds_write_b32 v130, v131 offset:4624
.LBB0_383:
	s_or_b64 exec, exec, s[2:3]
	s_waitcnt lgkmcnt(0)
	v_lshlrev_b64 v[132:133], 5, v[224:225]
	v_lshl_add_u64 v[132:133], s[44:45], 0, v[132:133]
	s_mov_b64 s[2:3], 0x1400
	v_lshl_add_u64 v[136:137], v[132:133], 0, s[2:3]
	v_add_co_u32_e32 v132, vcc, 0x1000, v132
	s_nop 1
	v_addc_co_u32_e32 v133, vcc, 0, v133, vcc
	global_load_dwordx4 v[132:135], v[132:133], off offset:1024
	s_nop 0
	global_load_dwordx4 v[136:139], v[136:137], off offset:16
	s_waitcnt vmcnt(1)
	v_mov_b32_e32 v140, v132
	s_waitcnt vmcnt(0)
	v_mov_b32_e32 v141, v136
	v_mov_b32_e32 v136, v133
	v_mov_b32_e32 v132, v134
	v_mov_b32_e32 v133, v138
	v_mov_b32_e32 v138, v135
	v_pk_add_f32 v[134:135], v[140:141], v[136:137]
	v_pk_add_f32 v[132:133], v[132:133], v[138:139]
	s_nop 0
	v_pk_add_f32 v[132:133], v[134:135], v[132:133]
	s_nop 0
	v_add_f32_e32 v131, v132, v133
	v_mov_b32_e32 v132, 0x358637bd
	v_fmamk_f32 v131, v131, 0x3a000000, v132
	v_mul_f32_e32 v132, 0x4b800000, v131
	v_cmp_gt_f32_e32 vcc, s92, v131
	s_nop 1
	v_cndmask_b32_e32 v131, v131, v132, vcc
	v_rsq_f32_e32 v131, v131
	s_nop 0
	v_mul_f32_e32 v132, 0x45800000, v131
	v_cndmask_b32_e32 v140, v131, v132, vcc
	v_pk_mul_f32 v[132:133], v[46:47], v[140:141] op_sel_hi:[1,0]
	v_pk_mul_f32 v[134:135], v[44:45], v[140:141] op_sel_hi:[1,0]
	v_pk_mul_f32 v[138:139], v[36:37], v[140:141] op_sel_hi:[1,0]
	v_mul_f32_e32 v131, v135, v135
	v_mul_f32_e32 v133, v133, v133
	v_pk_mul_f32 v[136:137], v[38:39], v[140:141] op_sel_hi:[1,0]
	v_mul_f32_e32 v135, v139, v139
	v_fmac_f32_e32 v131, v134, v134
	v_fmac_f32_e32 v133, v132, v132
	v_mul_f32_e32 v137, v137, v137
	v_fmac_f32_e32 v135, v138, v138
	v_add_f32_e32 v131, v131, v133
	v_add_f32_e32 v131, v135, v131
	v_fmac_f32_e32 v137, v136, v136
	v_add_f32_e32 v131, v137, v131
	v_mov_b32_e32 v132, v131
	s_nop 1
	v_permlane16_swap_b32_e32 v131, v132
	v_add_f32_e32 v131, v131, v132
	v_mov_b32_e32 v132, v131
	s_nop 1
	v_permlane32_swap_b32_e32 v131, v132
	s_and_saveexec_b64 s[2:3], s[8:9]
	s_cbranch_execz .LBB0_385
	s_waitcnt lgkmcnt(0)
	v_add_f32_e32 v131, v131, v132
	ds_write_b32 v130, v131 offset:5120
.LBB0_385:
	s_or_b64 exec, exec, s[2:3]
	v_mov_b32_e32 v141, v140
	s_waitcnt lgkmcnt(0)
	v_mov_b32_e32 v132, v140
	v_mov_b32_e32 v133, v140
	v_pk_mul_f32 v[134:135], v[14:15], v[132:133]
	v_pk_mul_f32 v[136:137], v[12:13], v[140:141]
	v_pk_mul_f32 v[138:139], v[8:9], v[140:141]
	v_mul_f32_e32 v131, v137, v137
	v_mul_f32_e32 v135, v135, v135
	v_pk_mul_f32 v[132:133], v[10:11], v[132:133]
	v_fmac_f32_e32 v131, v136, v136
	v_fmac_f32_e32 v135, v134, v134
	v_mul_f32_e32 v134, v139, v139
	v_add_f32_e32 v131, v131, v135
	v_fmac_f32_e32 v134, v138, v138
	v_mul_f32_e32 v133, v133, v133
	v_add_f32_e32 v131, v134, v131
	v_fmac_f32_e32 v133, v132, v132
	v_add_f32_e32 v131, v133, v131
	v_mov_b32_e32 v132, v131
	s_nop 1
	v_permlane16_swap_b32_e32 v131, v132
	v_add_f32_e32 v131, v131, v132
	v_mov_b32_e32 v132, v131
	s_nop 1
	v_permlane32_swap_b32_e32 v131, v132
	s_and_saveexec_b64 s[2:3], s[8:9]
	s_cbranch_execz .LBB0_387
	s_waitcnt lgkmcnt(0)
	v_add_f32_e32 v131, v131, v132
	ds_write_b32 v130, v131 offset:5136
.LBB0_387:
	s_or_b64 exec, exec, s[2:3]
	s_waitcnt lgkmcnt(0)
	v_lshlrev_b64 v[132:133], 5, v[224:225]
	v_lshl_add_u64 v[132:133], s[44:45], 0, v[132:133]
	s_mov_b64 s[2:3], 0x1600
	v_lshl_add_u64 v[136:137], v[132:133], 0, s[2:3]
	v_add_co_u32_e32 v132, vcc, 0x1000, v132
	s_nop 1
	v_addc_co_u32_e32 v133, vcc, 0, v133, vcc
	global_load_dwordx4 v[132:135], v[132:133], off offset:1536
	s_nop 0
	global_load_dwordx4 v[136:139], v[136:137], off offset:16
	s_waitcnt vmcnt(1)
	v_mov_b32_e32 v158, v132
	s_waitcnt vmcnt(0)
	v_mov_b32_e32 v159, v136
	v_mov_b32_e32 v136, v133
	v_mov_b32_e32 v132, v134
	v_mov_b32_e32 v133, v138
	v_mov_b32_e32 v138, v135
	v_pk_add_f32 v[134:135], v[158:159], v[136:137]
	v_pk_add_f32 v[132:133], v[132:133], v[138:139]
	s_nop 0
	v_pk_add_f32 v[132:133], v[134:135], v[132:133]
	s_nop 0
	v_add_f32_e32 v131, v132, v133
	v_mov_b32_e32 v132, 0x358637bd
	v_fmamk_f32 v131, v131, 0x3a000000, v132
	v_mul_f32_e32 v132, 0x4b800000, v131
	v_cmp_gt_f32_e32 vcc, s92, v131
	s_nop 1
	v_cndmask_b32_e32 v131, v131, v132, vcc
	v_rsq_f32_e32 v131, v131
	s_nop 0
	v_mul_f32_e32 v132, 0x45800000, v131
	v_cndmask_b32_e32 v136, v131, v132, vcc
	v_pk_mul_f32 v[132:133], v[30:31], v[136:137] op_sel_hi:[1,0]
	v_pk_mul_f32 v[134:135], v[28:29], v[136:137] op_sel_hi:[1,0]
	v_pk_mul_f32 v[158:159], v[20:21], v[136:137] op_sel_hi:[1,0]
	v_mul_f32_e32 v131, v135, v135
	v_mul_f32_e32 v133, v133, v133
	v_pk_mul_f32 v[138:139], v[22:23], v[136:137] op_sel_hi:[1,0]
	v_mul_f32_e32 v135, v159, v159
	v_fmac_f32_e32 v131, v134, v134
	v_fmac_f32_e32 v133, v132, v132
	v_mul_f32_e32 v137, v139, v139
	v_fmac_f32_e32 v135, v158, v158
	v_add_f32_e32 v131, v131, v133
	v_add_f32_e32 v131, v135, v131
	v_fmac_f32_e32 v137, v138, v138
	v_add_f32_e32 v131, v137, v131
	v_mov_b32_e32 v132, v131
	s_nop 1
	v_permlane16_swap_b32_e32 v131, v132
	v_add_f32_e32 v131, v131, v132
	v_mov_b32_e32 v132, v131
	s_nop 1
	v_permlane32_swap_b32_e32 v131, v132
	s_and_saveexec_b64 s[2:3], s[8:9]
	s_cbranch_execz .LBB0_389
	s_waitcnt lgkmcnt(0)
	v_add_f32_e32 v131, v131, v132
	ds_write_b32 v130, v131 offset:5632

.LBB0_992:
	s_add_i32 s12, s14, 0x800
	s_cmpk_gt_i32 s14, 0x7ff
	s_mov_b64 s[10:11], -1
	s_cbranch_scc0 .LBB0_998
	s_cmpk_gt_u32 s12, 0x1fff
	s_cbranch_scc0 .LBB0_995
	s_load_dwordx2 s[16:17], s[88:89], 0x90
	s_add_i32 s10, s14, 0xe800
	s_and_b32 s11, s10, 0xffc0
	s_lshl_b32 s10, s14, 6
	s_and_b32 s10, s10, 0xfc0
	s_lshl_b32 s13, s10, 2
	s_waitcnt lgkmcnt(0)
	s_add_u32 s16, s16, s13
	v_or_b32_e32 v4, s11, v65
	s_addc_u32 s17, s17, 0
	v_lshlrev_b32_e32 v208, 2, v64
	v_lshl_add_u64 v[0:1], s[16:17], 0, v[208:209]
	v_lshlrev_b32_e32 v208, 14, v4
	v_lshl_add_u64 v[2:3], v[0:1], 0, v[208:209]
	v_or_b32_e32 v63, 4, v4
	v_or_b32_e32 v71, 8, v4
	v_or_b32_e32 v86, 12, v4
	v_or_b32_e32 v87, 16, v4
	v_or_b32_e32 v88, 20, v4
	v_or_b32_e32 v89, 24, v4
	v_or_b32_e32 v90, 28, v4
	v_or_b32_e32 v91, 32, v4
	v_or_b32_e32 v92, 36, v4
	v_or_b32_e32 v93, 40, v4
	v_or_b32_e32 v94, 44, v4
	v_or_b32_e32 v95, 48, v4
	v_or_b32_e32 v96, 52, v4
	v_or_b32_e32 v97, 56, v4
	v_or_b32_e32 v98, 60, v4
	v_lshlrev_b32_e32 v4, 2, v4
	global_load_dwordx4 v[6:9], v[2:3], off
	global_load_dword v62, v4, s[4:5]
	v_lshlrev_b32_e32 v208, 14, v63
	v_lshl_add_u64 v[2:3], v[0:1], 0, v[208:209]
	global_load_dwordx4 v[10:13], v[2:3], off
	v_lshlrev_b32_e32 v208, 14, v71
	v_lshl_add_u64 v[2:3], v[0:1], 0, v[208:209]
	global_load_dwordx4 v[14:17], v[2:3], off
	v_lshlrev_b32_e32 v208, 14, v86
	v_lshl_add_u64 v[2:3], v[0:1], 0, v[208:209]
	global_load_dwordx4 v[18:21], v[2:3], off
	v_lshlrev_b32_e32 v208, 14, v87
	v_lshl_add_u64 v[2:3], v[0:1], 0, v[208:209]
	global_load_dwordx4 v[22:25], v[2:3], off
	v_lshlrev_b32_e32 v208, 14, v88
	v_lshl_add_u64 v[2:3], v[0:1], 0, v[208:209]
	global_load_dwordx4 v[26:29], v[2:3], off
	v_lshlrev_b32_e32 v208, 14, v89
	v_lshl_add_u64 v[2:3], v[0:1], 0, v[208:209]
	global_load_dwordx4 v[30:33], v[2:3], off
	v_lshlrev_b32_e32 v208, 14, v90
	v_lshl_add_u64 v[2:3], v[0:1], 0, v[208:209]
	global_load_dwordx4 v[34:37], v[2:3], off
	v_lshlrev_b32_e32 v208, 14, v91
	v_lshl_add_u64 v[2:3], v[0:1], 0, v[208:209]
	global_load_dwordx4 v[38:41], v[2:3], off
	v_lshlrev_b32_e32 v208, 14, v92
	v_lshl_add_u64 v[2:3], v[0:1], 0, v[208:209]
	global_load_dwordx4 v[42:45], v[2:3], off
	v_lshlrev_b32_e32 v208, 14, v93
	v_lshl_add_u64 v[2:3], v[0:1], 0, v[208:209]
	global_load_dwordx4 v[46:49], v[2:3], off
	v_lshlrev_b32_e32 v208, 14, v94
	v_lshl_add_u64 v[2:3], v[0:1], 0, v[208:209]
	global_load_dwordx4 v[50:53], v[2:3], off
	v_lshlrev_b32_e32 v208, 14, v95
	v_lshl_add_u64 v[2:3], v[0:1], 0, v[208:209]
	global_load_dwordx4 v[54:57], v[2:3], off
	v_lshlrev_b32_e32 v208, 14, v96
	v_lshl_add_u64 v[2:3], v[0:1], 0, v[208:209]
	global_load_dwordx4 v[58:61], v[2:3], off
	v_lshlrev_b32_e32 v208, 14, v97
	v_lshl_add_u64 v[2:3], v[0:1], 0, v[208:209]
	global_load_dwordx4 v[82:85], v[2:3], off
	v_lshlrev_b32_e32 v208, 14, v98
	v_lshl_add_u64 v[0:1], v[0:1], 0, v[208:209]
	global_load_dwordx4 v[0:3], v[0:1], off
	s_lshl_b32 s28, s11, 1
	v_lshlrev_b32_e32 v176, 2, v63
	global_load_dword v160, v176, s[4:5]
	v_lshlrev_b32_e32 v176, 2, v71
	global_load_dword v161, v176, s[4:5]
	v_lshlrev_b32_e32 v176, 2, v86
	global_load_dword v162, v176, s[4:5]
	v_lshlrev_b32_e32 v176, 2, v87
	global_load_dword v163, v176, s[4:5]
	v_lshlrev_b32_e32 v176, 2, v88
	global_load_dword v164, v176, s[4:5]
	v_lshlrev_b32_e32 v176, 2, v89
	global_load_dword v165, v176, s[4:5]
	v_lshlrev_b32_e32 v176, 2, v90
	global_load_dword v166, v176, s[4:5]
	v_lshlrev_b32_e32 v176, 2, v91
	global_load_dword v167, v176, s[4:5]
	v_lshlrev_b32_e32 v176, 2, v92
	global_load_dword v168, v176, s[4:5]
	v_lshlrev_b32_e32 v176, 2, v93
	global_load_dword v169, v176, s[4:5]
	v_lshlrev_b32_e32 v176, 2, v94
	global_load_dword v170, v176, s[4:5]
	v_lshlrev_b32_e32 v176, 2, v95
	global_load_dword v171, v176, s[4:5]
	v_lshlrev_b32_e32 v176, 2, v96
	global_load_dword v172, v176, s[4:5]
	v_lshlrev_b32_e32 v176, 2, v97
	global_load_dword v173, v176, s[4:5]
	v_lshlrev_b32_e32 v176, 2, v98
	global_load_dword v174, v176, s[4:5]
	s_waitcnt vmcnt(0)
	v_pk_mul_f32 v[4:5], v[8:9], v[62:63] op_sel_hi:[1,0]
	v_lshlrev_b32_e32 v8, 2, v63
	v_pk_mul_f32 v[6:7], v[6:7], v[62:63] op_sel_hi:[1,0]
	v_mov_b32_e32 v62, v160
	s_waitcnt vmcnt(0)
	v_pk_mul_f32 v[8:9], v[12:13], v[62:63] op_sel_hi:[1,0]
	v_lshlrev_b32_e32 v12, 2, v71
	v_pk_mul_f32 v[10:11], v[10:11], v[62:63] op_sel_hi:[1,0]
	v_mov_b32_e32 v62, v161
	v_lshlrev_b32_e32 v71, 2, v98
	s_waitcnt vmcnt(0)
	v_pk_mul_f32 v[12:13], v[16:17], v[62:63] op_sel_hi:[1,0]
	v_lshlrev_b32_e32 v16, 2, v86
	v_pk_mul_f32 v[14:15], v[14:15], v[62:63] op_sel_hi:[1,0]
	v_mov_b32_e32 v62, v162
	s_waitcnt vmcnt(0)
	v_pk_mul_f32 v[16:17], v[20:21], v[62:63] op_sel_hi:[1,0]
	v_lshlrev_b32_e32 v20, 2, v87
	v_pk_mul_f32 v[18:19], v[18:19], v[62:63] op_sel_hi:[1,0]
	v_mov_b32_e32 v62, v163
	s_waitcnt vmcnt(0)
	v_pk_mul_f32 v[20:21], v[24:25], v[62:63] op_sel_hi:[1,0]
	v_lshlrev_b32_e32 v24, 2, v88
	v_pk_mul_f32 v[22:23], v[22:23], v[62:63] op_sel_hi:[1,0]
	v_mov_b32_e32 v62, v164
	s_waitcnt vmcnt(0)
	v_pk_mul_f32 v[24:25], v[28:29], v[62:63] op_sel_hi:[1,0]
	v_lshlrev_b32_e32 v28, 2, v89
	v_pk_mul_f32 v[26:27], v[26:27], v[62:63] op_sel_hi:[1,0]
	v_mov_b32_e32 v62, v165
	s_waitcnt vmcnt(0)
	v_pk_mul_f32 v[28:29], v[32:33], v[62:63] op_sel_hi:[1,0]
	v_lshlrev_b32_e32 v32, 2, v90
	v_pk_mul_f32 v[30:31], v[30:31], v[62:63] op_sel_hi:[1,0]
	v_mov_b32_e32 v62, v166
	s_waitcnt vmcnt(0)
	v_pk_mul_f32 v[32:33], v[36:37], v[62:63] op_sel_hi:[1,0]
	v_lshlrev_b32_e32 v36, 2, v91
	v_pk_mul_f32 v[34:35], v[34:35], v[62:63] op_sel_hi:[1,0]
	v_mov_b32_e32 v62, v167
	s_waitcnt vmcnt(0)
	v_pk_mul_f32 v[36:37], v[40:41], v[62:63] op_sel_hi:[1,0]
	v_lshlrev_b32_e32 v40, 2, v92
	v_mov_b32_e32 v40, v168
	v_pk_mul_f32 v[38:39], v[38:39], v[62:63] op_sel_hi:[1,0]
	s_waitcnt vmcnt(0)
	v_pk_mul_f32 v[44:45], v[44:45], v[40:41] op_sel_hi:[1,0]
	v_pk_mul_f32 v[40:41], v[42:43], v[40:41] op_sel_hi:[1,0]
	v_lshlrev_b32_e32 v42, 2, v93
	v_mov_b32_e32 v42, v169
	s_waitcnt vmcnt(0)
	v_pk_mul_f32 v[48:49], v[48:49], v[42:43] op_sel_hi:[1,0]
	v_pk_mul_f32 v[42:43], v[46:47], v[42:43] op_sel_hi:[1,0]
	v_lshlrev_b32_e32 v46, 2, v94
	v_mov_b32_e32 v46, v170
	s_waitcnt vmcnt(0)
	v_pk_mul_f32 v[52:53], v[52:53], v[46:47] op_sel_hi:[1,0]
	v_pk_mul_f32 v[46:47], v[50:51], v[46:47] op_sel_hi:[1,0]
	v_lshlrev_b32_e32 v50, 2, v95
	v_mov_b32_e32 v50, v171
	s_waitcnt vmcnt(0)
	v_pk_mul_f32 v[56:57], v[56:57], v[50:51] op_sel_hi:[1,0]
	v_pk_mul_f32 v[50:51], v[54:55], v[50:51] op_sel_hi:[1,0]
	v_lshlrev_b32_e32 v54, 2, v96
	v_mov_b32_e32 v54, v172
	s_waitcnt vmcnt(0)
	v_pk_mul_f32 v[60:61], v[60:61], v[54:55] op_sel_hi:[1,0]
	v_pk_mul_f32 v[54:55], v[58:59], v[54:55] op_sel_hi:[1,0]
	v_lshlrev_b32_e32 v58, 2, v97
	v_mov_b32_e32 v58, v173
	s_waitcnt vmcnt(0)
	v_pk_mul_f32 v[62:63], v[84:85], v[58:59] op_sel_hi:[1,0]
	v_pk_mul_f32 v[58:59], v[82:83], v[58:59] op_sel_hi:[1,0]
	v_mov_b32_e32 v82, v174
	ds_write2_b32 v72, v6, v7 offset1:1
	ds_write2_b32 v72, v4, v5 offset0:2 offset1:3
	v_add_u32_e32 v4, 0x410, v72
	ds_write2_b32 v4, v10, v11 offset1:1
	v_add_u32_e32 v4, 0x418, v72
	ds_write2_b32 v4, v8, v9 offset1:1
	v_add_u32_e32 v4, 0x820, v72
	ds_write2_b32 v4, v14, v15 offset1:1
	v_add_u32_e32 v4, 0x828, v72
	ds_write2_b32 v4, v12, v13 offset1:1
	v_add_u32_e32 v4, 0xc30, v72
	ds_write2_b32 v4, v18, v19 offset1:1
	v_add_u32_e32 v4, 0xc38, v72
	ds_write2_b32 v4, v16, v17 offset1:1
	v_add_u32_e32 v4, 0x1040, v72
	ds_write2_b32 v4, v22, v23 offset1:1
	v_add_u32_e32 v4, 0x1048, v72
	ds_write2_b32 v4, v20, v21 offset1:1
	v_add_u32_e32 v4, 0x1450, v72
	ds_write2_b32 v4, v26, v27 offset1:1
	v_add_u32_e32 v4, 0x1458, v72
	ds_write2_b32 v4, v24, v25 offset1:1
	v_add_u32_e32 v4, 0x1860, v72
	ds_write2_b32 v4, v30, v31 offset1:1
	v_add_u32_e32 v4, 0x1868, v72
	ds_write2_b32 v4, v28, v29 offset1:1
	v_add_u32_e32 v4, 0x1c70, v72
	ds_write2_b32 v4, v34, v35 offset1:1
	v_add_u32_e32 v4, 0x1c78, v72
	ds_write2_b32 v4, v32, v33 offset1:1
	v_add_u32_e32 v4, 0x2080, v72
	ds_write2_b32 v4, v38, v39 offset1:1
	v_add_u32_e32 v4, 0x2088, v72
	ds_write2_b32 v4, v36, v37 offset1:1
	v_add_u32_e32 v4, 0x2490, v72
	ds_write2_b32 v4, v40, v41 offset1:1
	v_add_u32_e32 v4, 0x2498, v72
	ds_write2_b32 v4, v44, v45 offset1:1
	v_add_u32_e32 v4, 0x28a0, v72
	ds_write2_b32 v4, v42, v43 offset1:1
	v_add_u32_e32 v4, 0x28a8, v72
	ds_write2_b32 v4, v48, v49 offset1:1
	v_add_u32_e32 v4, 0x2cb0, v72
	ds_write2_b32 v4, v46, v47 offset1:1
	v_add_u32_e32 v4, 0x2cb8, v72
	ds_write2_b32 v4, v52, v53 offset1:1
	v_add_u32_e32 v4, 0x30c0, v72
	ds_write2_b32 v4, v50, v51 offset1:1
	v_add_u32_e32 v4, 0x30c8, v72
	ds_write2_b32 v4, v56, v57 offset1:1
	v_add_u32_e32 v4, 0x34d0, v72
	ds_write2_b32 v4, v54, v55 offset1:1
	v_add_u32_e32 v4, 0x34d8, v72
	ds_write2_b32 v4, v60, v61 offset1:1
	v_add_u32_e32 v4, 0x38e0, v72
	ds_write2_b32 v4, v58, v59 offset1:1
	v_add_u32_e32 v4, 0x38e8, v72
	ds_write2_b32 v4, v62, v63 offset1:1
	v_add_u32_e32 v4, 0x3cf0, v72
	s_waitcnt vmcnt(0)
	v_pk_mul_f32 v[0:1], v[0:1], v[82:83] op_sel_hi:[1,0]
	v_pk_mul_f32 v[2:3], v[2:3], v[82:83] op_sel_hi:[1,0]
	ds_write2_b32 v4, v0, v1 offset1:1
	v_add_u32_e32 v0, 0x3cf8, v72
	ds_write2_b32 v0, v2, v3 offset1:1
	s_waitcnt lgkmcnt(0)
	ds_read2_b32 v[2:3], v74 offset0:65 offset1:73
	ds_read2_b32 v[8:9], v74 offset1:8
	ds_read2_b32 v[10:11], v74 offset0:130 offset1:138
	ds_read2_b32 v[12:13], v74 offset0:195 offset1:203
	v_lshl_add_u64 v[0:1], v[66:67], 0, s[28:29]
	s_waitcnt lgkmcnt(3)
	v_bfe_u32 v5, v2, 16, 1
	s_waitcnt lgkmcnt(2)
	v_bfe_u32 v4, v8, 16, 1
	v_add3_u32 v4, v8, v4, s85
	v_lshrrev_b32_e32 v4, 16, v4
	v_add3_u32 v2, v2, v5, s85
	v_and_or_b32 v4, v2, s1, v4
	s_waitcnt lgkmcnt(1)
	v_bfe_u32 v2, v10, 16, 1
	v_add3_u32 v2, v10, v2, s85
	s_waitcnt lgkmcnt(0)
	v_bfe_u32 v5, v12, 16, 1
	v_lshrrev_b32_e32 v2, 16, v2
	v_add3_u32 v5, v12, v5, s85
	v_and_or_b32 v5, v5, s1, v2
	v_add_u32_e32 v2, 0x400, v74
	ds_read2_b32 v[14:15], v2 offset0:4 offset1:12
	ds_read2_b32 v[16:17], v2 offset0:69 offset1:77
	ds_read2_b32 v[18:19], v2 offset0:134 offset1:142
	ds_read2_b32 v[20:21], v2 offset0:199 offset1:207
	s_waitcnt lgkmcnt(3)
	v_bfe_u32 v6, v14, 16, 1
	v_add3_u32 v6, v14, v6, s85
	s_waitcnt lgkmcnt(2)
	v_bfe_u32 v7, v16, 16, 1
	v_lshrrev_b32_e32 v6, 16, v6
	v_add3_u32 v7, v16, v7, s85
	v_and_or_b32 v6, v7, s1, v6
	s_waitcnt lgkmcnt(1)
	v_bfe_u32 v7, v18, 16, 1
	v_add3_u32 v7, v18, v7, s85
	s_waitcnt lgkmcnt(0)
	v_bfe_u32 v8, v20, 16, 1
	v_lshrrev_b32_e32 v7, 16, v7
	v_add3_u32 v8, v20, v8, s85
	v_and_or_b32 v7, v8, s1, v7
	v_or_b32_e32 v8, s10, v73
	v_lshlrev_b32_e32 v208, 12, v8
	v_lshl_add_u64 v[22:23], v[0:1], 0, v[208:209]
	global_store_dwordx4 v[22:23], v[4:7], off
	s_nop 1
	v_bfe_u32 v4, v9, 16, 1
	v_add3_u32 v4, v9, v4, s85
	v_bfe_u32 v5, v3, 16, 1
	v_lshrrev_b32_e32 v4, 16, v4
	v_add3_u32 v3, v3, v5, s85
	v_and_or_b32 v4, v3, s1, v4
	v_bfe_u32 v3, v11, 16, 1
	v_add3_u32 v3, v11, v3, s85
	v_bfe_u32 v5, v13, 16, 1
	v_lshrrev_b32_e32 v3, 16, v3
	v_add3_u32 v5, v13, v5, s85
	v_and_or_b32 v5, v5, s1, v3
	v_bfe_u32 v3, v15, 16, 1
	v_add3_u32 v3, v15, v3, s85
	v_bfe_u32 v6, v17, 16, 1
	v_lshrrev_b32_e32 v3, 16, v3
	v_add3_u32 v6, v17, v6, s85
	v_and_or_b32 v6, v6, s1, v3
	v_bfe_u32 v3, v19, 16, 1
	v_add3_u32 v3, v19, v3, s85
	v_bfe_u32 v7, v21, 16, 1
	v_lshrrev_b32_e32 v3, 16, v3
	v_add3_u32 v7, v21, v7, s85
	v_and_or_b32 v7, v7, s1, v3
	v_or_b32_e32 v3, s10, v75
	v_lshlrev_b32_e32 v208, 12, v3
	v_lshl_add_u64 v[8:9], v[0:1], 0, v[208:209]
	global_store_dwordx4 v[8:9], v[4:7], off
	ds_read2_b32 v[8:9], v74 offset0:81 offset1:89
	ds_read2_b32 v[10:11], v74 offset0:16 offset1:24
	ds_read2_b32 v[12:13], v74 offset0:146 offset1:154
	ds_read2_b32 v[14:15], v74 offset0:211 offset1:219
	ds_read2_b32 v[16:17], v2 offset0:20 offset1:28
	ds_read2_b32 v[18:19], v2 offset0:85 offset1:93
	ds_read2_b32 v[20:21], v2 offset0:150 offset1:158
	ds_read2_b32 v[22:23], v2 offset0:215 offset1:223
	s_waitcnt lgkmcnt(7)
	v_bfe_u32 v4, v8, 16, 1
	s_waitcnt lgkmcnt(6)
	v_bfe_u32 v3, v10, 16, 1
	v_add3_u32 v3, v10, v3, s85
	v_lshrrev_b32_e32 v3, 16, v3
	v_add3_u32 v4, v8, v4, s85
	v_and_or_b32 v4, v4, s1, v3
	s_waitcnt lgkmcnt(5)
	v_bfe_u32 v3, v12, 16, 1
	v_add3_u32 v3, v12, v3, s85
	s_waitcnt lgkmcnt(4)
	v_bfe_u32 v5, v14, 16, 1
	v_lshrrev_b32_e32 v3, 16, v3
	v_add3_u32 v5, v14, v5, s85
	v_and_or_b32 v5, v5, s1, v3
	s_waitcnt lgkmcnt(3)
	v_bfe_u32 v3, v16, 16, 1
	v_add3_u32 v3, v16, v3, s85
	s_waitcnt lgkmcnt(2)
	v_bfe_u32 v6, v18, 16, 1
	v_lshrrev_b32_e32 v3, 16, v3
	v_add3_u32 v6, v18, v6, s85
	v_and_or_b32 v6, v6, s1, v3
	s_waitcnt lgkmcnt(1)
	v_bfe_u32 v3, v20, 16, 1
	v_add3_u32 v3, v20, v3, s85
	s_waitcnt lgkmcnt(0)
	v_bfe_u32 v7, v22, 16, 1
	v_lshrrev_b32_e32 v3, 16, v3
	v_add3_u32 v7, v22, v7, s85
	v_and_or_b32 v7, v7, s1, v3
	v_or_b32_e32 v3, s10, v76
	v_lshlrev_b32_e32 v208, 12, v3
	v_lshl_add_u64 v[24:25], v[0:1], 0, v[208:209]
	v_bfe_u32 v3, v11, 16, 1
	global_store_dwordx4 v[24:25], v[4:7], off
	v_add3_u32 v3, v11, v3, s85
	v_lshrrev_b32_e32 v3, 16, v3
	v_bfe_u32 v4, v9, 16, 1
	v_add3_u32 v4, v9, v4, s85
	v_and_or_b32 v4, v4, s1, v3
	v_bfe_u32 v3, v13, 16, 1
	v_add3_u32 v3, v13, v3, s85
	v_bfe_u32 v5, v15, 16, 1
	v_lshrrev_b32_e32 v3, 16, v3
	v_add3_u32 v5, v15, v5, s85
	v_and_or_b32 v5, v5, s1, v3
	v_bfe_u32 v3, v17, 16, 1
	v_add3_u32 v3, v17, v3, s85
	v_bfe_u32 v6, v19, 16, 1
	v_lshrrev_b32_e32 v3, 16, v3
	v_add3_u32 v6, v19, v6, s85
	v_and_or_b32 v6, v6, s1, v3
	v_bfe_u32 v3, v21, 16, 1
	v_add3_u32 v3, v21, v3, s85
	v_bfe_u32 v7, v23, 16, 1
	v_lshrrev_b32_e32 v3, 16, v3
	v_add3_u32 v7, v23, v7, s85
	v_and_or_b32 v7, v7, s1, v3
	v_or_b32_e32 v3, s10, v77
	v_lshlrev_b32_e32 v208, 12, v3
	v_lshl_add_u64 v[8:9], v[0:1], 0, v[208:209]
	global_store_dwordx4 v[8:9], v[4:7], off
	ds_read2_b32 v[8:9], v74 offset0:97 offset1:105
	ds_read2_b32 v[10:11], v74 offset0:32 offset1:40
	ds_read2_b32 v[12:13], v74 offset0:162 offset1:170
	ds_read2_b32 v[14:15], v74 offset0:227 offset1:235
	ds_read2_b32 v[16:17], v2 offset0:36 offset1:44
	ds_read2_b32 v[18:19], v2 offset0:101 offset1:109
	ds_read2_b32 v[20:21], v2 offset0:166 offset1:174
	ds_read2_b32 v[22:23], v2 offset0:231 offset1:239
	s_waitcnt lgkmcnt(7)
	v_bfe_u32 v4, v8, 16, 1
	s_waitcnt lgkmcnt(6)
	v_bfe_u32 v3, v10, 16, 1
	v_add3_u32 v3, v10, v3, s85
	v_lshrrev_b32_e32 v3, 16, v3
	v_add3_u32 v4, v8, v4, s85
	v_and_or_b32 v4, v4, s1, v3
	s_waitcnt lgkmcnt(5)
	v_bfe_u32 v3, v12, 16, 1
	v_add3_u32 v3, v12, v3, s85
	s_waitcnt lgkmcnt(4)
	v_bfe_u32 v5, v14, 16, 1
	v_lshrrev_b32_e32 v3, 16, v3
	v_add3_u32 v5, v14, v5, s85
	v_and_or_b32 v5, v5, s1, v3
	s_waitcnt lgkmcnt(3)
	v_bfe_u32 v3, v16, 16, 1
	v_add3_u32 v3, v16, v3, s85
	s_waitcnt lgkmcnt(2)
	v_bfe_u32 v6, v18, 16, 1
	v_lshrrev_b32_e32 v3, 16, v3
	v_add3_u32 v6, v18, v6, s85
	v_and_or_b32 v6, v6, s1, v3
	s_waitcnt lgkmcnt(1)
	v_bfe_u32 v3, v20, 16, 1
	v_add3_u32 v3, v20, v3, s85
	s_waitcnt lgkmcnt(0)
	v_bfe_u32 v7, v22, 16, 1
	v_lshrrev_b32_e32 v3, 16, v3
	v_add3_u32 v7, v22, v7, s85
	v_and_or_b32 v7, v7, s1, v3
	v_or_b32_e32 v3, s10, v78
	v_lshlrev_b32_e32 v208, 12, v3
	v_lshl_add_u64 v[24:25], v[0:1], 0, v[208:209]
	v_bfe_u32 v3, v11, 16, 1
	global_store_dwordx4 v[24:25], v[4:7], off
	v_add3_u32 v3, v11, v3, s85
	v_lshrrev_b32_e32 v3, 16, v3
	v_bfe_u32 v4, v9, 16, 1
	v_add3_u32 v4, v9, v4, s85
	v_and_or_b32 v4, v4, s1, v3
	v_bfe_u32 v3, v13, 16, 1
	v_add3_u32 v3, v13, v3, s85
	v_bfe_u32 v5, v15, 16, 1
	v_lshrrev_b32_e32 v3, 16, v3
	v_add3_u32 v5, v15, v5, s85
	v_and_or_b32 v5, v5, s1, v3
	v_bfe_u32 v3, v17, 16, 1
	v_add3_u32 v3, v17, v3, s85
	v_bfe_u32 v6, v19, 16, 1
	v_lshrrev_b32_e32 v3, 16, v3
	v_add3_u32 v6, v19, v6, s85
	v_and_or_b32 v6, v6, s1, v3
	v_bfe_u32 v3, v21, 16, 1
	v_add3_u32 v3, v21, v3, s85
	v_bfe_u32 v7, v23, 16, 1
	v_lshrrev_b32_e32 v3, 16, v3
	v_add3_u32 v7, v23, v7, s85
	v_and_or_b32 v7, v7, s1, v3
	v_or_b32_e32 v3, s10, v79
	v_lshlrev_b32_e32 v208, 12, v3
	v_lshl_add_u64 v[8:9], v[0:1], 0, v[208:209]
	global_store_dwordx4 v[8:9], v[4:7], off
	ds_read2_b32 v[8:9], v74 offset0:48 offset1:56
	ds_read2_b32 v[10:11], v74 offset0:113 offset1:121
	ds_read2_b32 v[12:13], v74 offset0:178 offset1:186
	ds_read2_b32 v[14:15], v74 offset0:243 offset1:251
	ds_read2_b32 v[16:17], v2 offset0:52 offset1:60
	ds_read2_b32 v[18:19], v2 offset0:117 offset1:125
	ds_read2_b32 v[20:21], v2 offset0:182 offset1:190
	ds_read2_b32 v[22:23], v2 offset0:247 offset1:255
	s_waitcnt lgkmcnt(7)
	v_bfe_u32 v3, v8, 16, 1
	v_add3_u32 v3, v8, v3, s85
	s_waitcnt lgkmcnt(6)
	v_bfe_u32 v4, v10, 16, 1
	v_lshrrev_b32_e32 v3, 16, v3
	v_add3_u32 v4, v10, v4, s85
	v_and_or_b32 v4, v4, s1, v3
	s_waitcnt lgkmcnt(5)
	v_bfe_u32 v3, v12, 16, 1
	v_add3_u32 v3, v12, v3, s85
	s_waitcnt lgkmcnt(4)
	v_bfe_u32 v5, v14, 16, 1
	v_lshrrev_b32_e32 v3, 16, v3
	v_add3_u32 v5, v14, v5, s85
	v_and_or_b32 v5, v5, s1, v3
	s_waitcnt lgkmcnt(3)
	v_bfe_u32 v3, v16, 16, 1
	v_add3_u32 v3, v16, v3, s85
	s_waitcnt lgkmcnt(2)
	v_bfe_u32 v6, v18, 16, 1
	v_lshrrev_b32_e32 v3, 16, v3
	v_add3_u32 v6, v18, v6, s85
	s_waitcnt lgkmcnt(1)
	v_bfe_u32 v2, v20, 16, 1
	v_and_or_b32 v6, v6, s1, v3
	v_add3_u32 v2, v20, v2, s85
	s_waitcnt lgkmcnt(0)
	v_bfe_u32 v3, v22, 16, 1
	v_lshrrev_b32_e32 v2, 16, v2
	v_add3_u32 v3, v22, v3, s85
	v_and_or_b32 v7, v3, s1, v2
	v_or_b32_e32 v2, s10, v80
	v_lshlrev_b32_e32 v208, 12, v2
	v_lshl_add_u64 v[2:3], v[0:1], 0, v[208:209]
	global_store_dwordx4 v[2:3], v[4:7], off
	v_bfe_u32 v2, v9, 16, 1
	v_add3_u32 v2, v9, v2, s85
	v_bfe_u32 v3, v11, 16, 1
	v_lshrrev_b32_e32 v2, 16, v2
	v_add3_u32 v3, v11, v3, s85
	v_and_or_b32 v2, v3, s1, v2
	v_bfe_u32 v3, v13, 16, 1
	v_add3_u32 v3, v13, v3, s85
	v_bfe_u32 v4, v15, 16, 1
	v_lshrrev_b32_e32 v3, 16, v3
	v_add3_u32 v4, v15, v4, s85
	v_and_or_b32 v3, v4, s1, v3
	v_bfe_u32 v4, v17, 16, 1
	v_add3_u32 v4, v17, v4, s85
	v_bfe_u32 v5, v19, 16, 1
	v_lshrrev_b32_e32 v4, 16, v4
	v_add3_u32 v5, v19, v5, s85
	v_and_or_b32 v4, v5, s1, v4
	v_bfe_u32 v5, v21, 16, 1
	v_add3_u32 v5, v21, v5, s85
	v_bfe_u32 v6, v23, 16, 1
	v_lshrrev_b32_e32 v5, 16, v5
	v_add3_u32 v6, v23, v6, s85
	v_and_or_b32 v5, v6, s1, v5
	v_or_b32_e32 v6, s10, v81
	v_lshlrev_b32_e32 v208, 12, v6
	v_lshl_add_u64 v[0:1], v[0:1], 0, v[208:209]
	global_store_dwordx4 v[0:1], v[2:5], off
	s_waitcnt lgkmcnt(0)
	s_mov_b64 s[10:11], 0
.LBB0_995:
	s_andn2_b64 vcc, exec, s[10:11]
	s_cbranch_vccnz .LBB0_997
	s_load_dwordx2 s[16:17], s[88:89], 0x70
	s_add_i32 s10, s14, 0xf800
	s_lshr_b32 s10, s10, 1
	s_and_b32 s11, s10, 0x7fc0
	s_lshl_b32 s10, s14, 6
	s_and_b32 s10, s10, 0x1fc0
	s_lshl_b32 s13, s10, 2
	v_or_b32_e32 v62, s11, v65
	s_waitcnt lgkmcnt(0)
	s_add_u32 s16, s16, s13
	s_addc_u32 s17, s17, 0
	v_lshlrev_b32_e32 v208, 2, v64
	v_mul_u32_u24_e32 v2, 0x2010, v62
	v_lshl_add_u64 v[0:1], s[16:17], 0, v[208:209]
	v_lshlrev_b32_e32 v208, 2, v2
	v_lshl_add_u64 v[2:3], v[0:1], 0, v[208:209]
	v_add_co_u32_e32 v4, vcc, s19, v2
	s_mov_b32 s13, 0x40000
	s_nop 0
	v_addc_co_u32_e32 v5, vcc, 0, v3, vcc
	global_load_dwordx4 v[6:9], v[2:3], off
	global_load_dwordx4 v[10:13], v[4:5], off offset:256
	v_add_co_u32_e32 v2, vcc, s13, v2
	v_lshlrev_b32_e32 v71, 2, v62
	s_nop 0
	v_addc_co_u32_e32 v3, vcc, 0, v3, vcc
	global_load_dwordx4 v[14:17], v[2:3], off offset:512
	v_add_u32_e32 v2, 0x60300, v208
	v_mov_b32_e32 v3, v209
	v_lshl_add_u64 v[2:3], v[0:1], 0, v[2:3]
	global_load_dwordx4 v[18:21], v[2:3], off
	v_add_u32_e32 v2, 0x80400, v208
	v_mov_b32_e32 v3, v209
	v_lshl_add_u64 v[2:3], v[0:1], 0, v[2:3]
	global_load_dwordx4 v[22:25], v[2:3], off
	v_add_u32_e32 v2, 0xa0500, v208
	v_mov_b32_e32 v3, v209
	v_lshl_add_u64 v[2:3], v[0:1], 0, v[2:3]
	global_load_dwordx4 v[26:29], v[2:3], off
	v_add_u32_e32 v2, 0xc0600, v208
	v_mov_b32_e32 v3, v209
	v_lshl_add_u64 v[2:3], v[0:1], 0, v[2:3]
	global_load_dwordx4 v[30:33], v[2:3], off
	v_add_u32_e32 v2, 0xe0700, v208
	v_mov_b32_e32 v3, v209
	v_lshl_add_u64 v[2:3], v[0:1], 0, v[2:3]
	global_load_dwordx4 v[34:37], v[2:3], off
	v_add_u32_e32 v2, 0x100800, v208
	v_mov_b32_e32 v3, v209
	v_lshl_add_u64 v[2:3], v[0:1], 0, v[2:3]
	global_load_dwordx4 v[38:41], v[2:3], off
	v_add_u32_e32 v2, 0x120900, v208
	v_mov_b32_e32 v3, v209
	v_lshl_add_u64 v[2:3], v[0:1], 0, v[2:3]
	global_load_dwordx4 v[42:45], v[2:3], off
	v_add_u32_e32 v2, 0x140a00, v208
	v_mov_b32_e32 v3, v209
	v_lshl_add_u64 v[2:3], v[0:1], 0, v[2:3]
	global_load_dwordx4 v[46:49], v[2:3], off
	v_add_u32_e32 v2, 0x160b00, v208
	v_mov_b32_e32 v3, v209
	v_lshl_add_u64 v[2:3], v[0:1], 0, v[2:3]
	global_load_dwordx4 v[50:53], v[2:3], off
	v_add_u32_e32 v2, 0x180c00, v208
	v_mov_b32_e32 v3, v209
	v_lshl_add_u64 v[2:3], v[0:1], 0, v[2:3]
	global_load_dwordx4 v[54:57], v[2:3], off
	v_add_u32_e32 v2, 0x1a0d00, v208
	v_mov_b32_e32 v3, v209
	v_lshl_add_u64 v[2:3], v[0:1], 0, v[2:3]
	global_load_dwordx4 v[58:61], v[2:3], off
	v_add_u32_e32 v2, 0x1c0e00, v208
	v_mov_b32_e32 v3, v209
	v_add_u32_e32 v208, 0x1e0f00, v208
	v_lshl_add_u64 v[2:3], v[0:1], 0, v[2:3]
	v_lshl_add_u64 v[0:1], v[0:1], 0, v[208:209]
	global_load_dwordx4 v[82:85], v[2:3], off
	s_nop 0
	global_load_dwordx4 v[0:3], v[0:1], off
	s_nop 0
	global_load_dword v62, v71, s[6:7]
	s_lshl_b32 s28, s11, 1
	global_load_dword v160, v71, s[6:7] offset:16
	global_load_dword v161, v71, s[6:7] offset:32
	global_load_dword v162, v71, s[6:7] offset:48
	global_load_dword v163, v71, s[6:7] offset:64
	global_load_dword v164, v71, s[6:7] offset:80
	global_load_dword v165, v71, s[6:7] offset:96
	global_load_dword v166, v71, s[6:7] offset:112
	global_load_dword v167, v71, s[6:7] offset:128
	global_load_dword v168, v71, s[6:7] offset:144
	global_load_dword v169, v71, s[6:7] offset:160
	global_load_dword v170, v71, s[6:7] offset:176
	global_load_dword v171, v71, s[6:7] offset:192
	global_load_dword v172, v71, s[6:7] offset:208
	global_load_dword v173, v71, s[6:7] offset:224
	global_load_dword v174, v71, s[6:7] offset:240
	s_waitcnt vmcnt(0)
	v_pk_mul_f32 v[4:5], v[8:9], v[62:63] op_sel_hi:[1,0]
	v_or_b32_e32 v8, 16, v71
	v_pk_mul_f32 v[6:7], v[6:7], v[62:63] op_sel_hi:[1,0]
	v_mov_b32_e32 v62, v160
	s_waitcnt vmcnt(0)
	v_pk_mul_f32 v[8:9], v[12:13], v[62:63] op_sel_hi:[1,0]
	v_or_b32_e32 v12, 32, v71
	v_pk_mul_f32 v[10:11], v[10:11], v[62:63] op_sel_hi:[1,0]
	v_mov_b32_e32 v62, v161
	s_waitcnt vmcnt(0)
	v_pk_mul_f32 v[12:13], v[16:17], v[62:63] op_sel_hi:[1,0]
	v_or_b32_e32 v16, 48, v71
	v_pk_mul_f32 v[14:15], v[14:15], v[62:63] op_sel_hi:[1,0]
	v_mov_b32_e32 v62, v162
	s_waitcnt vmcnt(0)
	v_pk_mul_f32 v[16:17], v[20:21], v[62:63] op_sel_hi:[1,0]
	v_or_b32_e32 v20, 64, v71
	v_pk_mul_f32 v[18:19], v[18:19], v[62:63] op_sel_hi:[1,0]
	v_mov_b32_e32 v62, v163
	s_waitcnt vmcnt(0)
	v_pk_mul_f32 v[20:21], v[24:25], v[62:63] op_sel_hi:[1,0]
	v_or_b32_e32 v24, 0x50, v71
	v_pk_mul_f32 v[22:23], v[22:23], v[62:63] op_sel_hi:[1,0]
	v_mov_b32_e32 v62, v164
	s_waitcnt vmcnt(0)
	v_pk_mul_f32 v[24:25], v[28:29], v[62:63] op_sel_hi:[1,0]
	v_or_b32_e32 v28, 0x60, v71
	v_pk_mul_f32 v[26:27], v[26:27], v[62:63] op_sel_hi:[1,0]
	v_mov_b32_e32 v62, v165
	s_waitcnt vmcnt(0)
	v_pk_mul_f32 v[28:29], v[32:33], v[62:63] op_sel_hi:[1,0]
	v_or_b32_e32 v32, 0x70, v71
	v_pk_mul_f32 v[30:31], v[30:31], v[62:63] op_sel_hi:[1,0]
	v_mov_b32_e32 v62, v166
	s_waitcnt vmcnt(0)
	v_pk_mul_f32 v[32:33], v[36:37], v[62:63] op_sel_hi:[1,0]
	v_or_b32_e32 v36, 0x80, v71
	v_pk_mul_f32 v[34:35], v[34:35], v[62:63] op_sel_hi:[1,0]
	v_mov_b32_e32 v62, v167
	s_waitcnt vmcnt(0)
	v_pk_mul_f32 v[36:37], v[40:41], v[62:63] op_sel_hi:[1,0]
	v_or_b32_e32 v40, 0x90, v71
	v_mov_b32_e32 v40, v168
	v_pk_mul_f32 v[38:39], v[38:39], v[62:63] op_sel_hi:[1,0]
	s_waitcnt vmcnt(0)
	v_pk_mul_f32 v[44:45], v[44:45], v[40:41] op_sel_hi:[1,0]
	v_pk_mul_f32 v[40:41], v[42:43], v[40:41] op_sel_hi:[1,0]
	v_or_b32_e32 v42, 0xa0, v71
	v_mov_b32_e32 v42, v169
	s_waitcnt vmcnt(0)
	v_pk_mul_f32 v[48:49], v[48:49], v[42:43] op_sel_hi:[1,0]
	v_pk_mul_f32 v[42:43], v[46:47], v[42:43] op_sel_hi:[1,0]
	v_or_b32_e32 v46, 0xb0, v71
	v_mov_b32_e32 v46, v170
	s_waitcnt vmcnt(0)
	v_pk_mul_f32 v[52:53], v[52:53], v[46:47] op_sel_hi:[1,0]
	v_pk_mul_f32 v[46:47], v[50:51], v[46:47] op_sel_hi:[1,0]
	v_or_b32_e32 v50, 0xc0, v71
	v_mov_b32_e32 v50, v171
	s_waitcnt vmcnt(0)
	v_pk_mul_f32 v[56:57], v[56:57], v[50:51] op_sel_hi:[1,0]
	v_pk_mul_f32 v[50:51], v[54:55], v[50:51] op_sel_hi:[1,0]
	v_or_b32_e32 v54, 0xd0, v71
	v_mov_b32_e32 v54, v172
	s_waitcnt vmcnt(0)
	v_pk_mul_f32 v[60:61], v[60:61], v[54:55] op_sel_hi:[1,0]
	v_pk_mul_f32 v[54:55], v[58:59], v[54:55] op_sel_hi:[1,0]
	v_or_b32_e32 v58, 0xe0, v71
	v_mov_b32_e32 v58, v173
	v_or_b32_e32 v71, 0xf0, v71
	s_waitcnt vmcnt(0)
	v_pk_mul_f32 v[62:63], v[84:85], v[58:59] op_sel_hi:[1,0]
	v_pk_mul_f32 v[58:59], v[82:83], v[58:59] op_sel_hi:[1,0]
	v_mov_b32_e32 v82, v174
	ds_write2_b32 v72, v6, v7 offset1:1
	ds_write2_b32 v72, v4, v5 offset0:2 offset1:3
	v_add_u32_e32 v4, 0x410, v72
	ds_write2_b32 v4, v10, v11 offset1:1
	v_add_u32_e32 v4, 0x418, v72
	ds_write2_b32 v4, v8, v9 offset1:1
	v_add_u32_e32 v4, 0x820, v72
	ds_write2_b32 v4, v14, v15 offset1:1
	v_add_u32_e32 v4, 0x828, v72
	ds_write2_b32 v4, v12, v13 offset1:1
	v_add_u32_e32 v4, 0xc30, v72
	ds_write2_b32 v4, v18, v19 offset1:1
	v_add_u32_e32 v4, 0xc38, v72
	ds_write2_b32 v4, v16, v17 offset1:1
	v_add_u32_e32 v4, 0x1040, v72
	ds_write2_b32 v4, v22, v23 offset1:1
	v_add_u32_e32 v4, 0x1048, v72
	ds_write2_b32 v4, v20, v21 offset1:1
	v_add_u32_e32 v4, 0x1450, v72
	ds_write2_b32 v4, v26, v27 offset1:1
	v_add_u32_e32 v4, 0x1458, v72
	ds_write2_b32 v4, v24, v25 offset1:1
	v_add_u32_e32 v4, 0x1860, v72
	ds_write2_b32 v4, v30, v31 offset1:1
	v_add_u32_e32 v4, 0x1868, v72
	ds_write2_b32 v4, v28, v29 offset1:1
	v_add_u32_e32 v4, 0x1c70, v72
	ds_write2_b32 v4, v34, v35 offset1:1
	v_add_u32_e32 v4, 0x1c78, v72
	ds_write2_b32 v4, v32, v33 offset1:1
	v_add_u32_e32 v4, 0x2080, v72
	ds_write2_b32 v4, v38, v39 offset1:1
	v_add_u32_e32 v4, 0x2088, v72
	ds_write2_b32 v4, v36, v37 offset1:1
	v_add_u32_e32 v4, 0x2490, v72
	ds_write2_b32 v4, v40, v41 offset1:1
	v_add_u32_e32 v4, 0x2498, v72
	ds_write2_b32 v4, v44, v45 offset1:1
	v_add_u32_e32 v4, 0x28a0, v72
	ds_write2_b32 v4, v42, v43 offset1:1
	v_add_u32_e32 v4, 0x28a8, v72
	ds_write2_b32 v4, v48, v49 offset1:1
	v_add_u32_e32 v4, 0x2cb0, v72
	ds_write2_b32 v4, v46, v47 offset1:1
	v_add_u32_e32 v4, 0x2cb8, v72
	ds_write2_b32 v4, v52, v53 offset1:1
	v_add_u32_e32 v4, 0x30c0, v72
	ds_write2_b32 v4, v50, v51 offset1:1
	v_add_u32_e32 v4, 0x30c8, v72
	ds_write2_b32 v4, v56, v57 offset1:1
	v_add_u32_e32 v4, 0x34d0, v72
	ds_write2_b32 v4, v54, v55 offset1:1
	v_add_u32_e32 v4, 0x34d8, v72
	ds_write2_b32 v4, v60, v61 offset1:1
	v_add_u32_e32 v4, 0x38e0, v72
	ds_write2_b32 v4, v58, v59 offset1:1
	v_add_u32_e32 v4, 0x38e8, v72
	ds_write2_b32 v4, v62, v63 offset1:1
	v_add_u32_e32 v4, 0x3cf0, v72
	s_waitcnt vmcnt(0)
	v_pk_mul_f32 v[0:1], v[0:1], v[82:83] op_sel_hi:[1,0]
	v_pk_mul_f32 v[2:3], v[2:3], v[82:83] op_sel_hi:[1,0]
	ds_write2_b32 v4, v0, v1 offset1:1
	v_add_u32_e32 v0, 0x3cf8, v72
	ds_write2_b32 v0, v2, v3 offset1:1
	s_waitcnt lgkmcnt(0)
	ds_read2_b32 v[2:3], v74 offset0:65 offset1:73
	ds_read2_b32 v[8:9], v74 offset1:8
	ds_read2_b32 v[10:11], v74 offset0:130 offset1:138
	ds_read2_b32 v[12:13], v74 offset0:195 offset1:203
	v_lshl_add_u64 v[0:1], v[68:69], 0, s[28:29]
	s_waitcnt lgkmcnt(3)
	v_bfe_u32 v5, v2, 16, 1
	s_waitcnt lgkmcnt(2)
	v_bfe_u32 v4, v8, 16, 1
	v_add3_u32 v4, v8, v4, s85
	v_lshrrev_b32_e32 v4, 16, v4
	v_add3_u32 v2, v2, v5, s85
	v_and_or_b32 v4, v2, s1, v4
	s_waitcnt lgkmcnt(1)
	v_bfe_u32 v2, v10, 16, 1
	v_add3_u32 v2, v10, v2, s85
	s_waitcnt lgkmcnt(0)
	v_bfe_u32 v5, v12, 16, 1
	v_lshrrev_b32_e32 v2, 16, v2
	v_add3_u32 v5, v12, v5, s85
	v_and_or_b32 v5, v5, s1, v2
	v_add_u32_e32 v2, 0x400, v74
	ds_read2_b32 v[14:15], v2 offset0:4 offset1:12
	ds_read2_b32 v[16:17], v2 offset0:69 offset1:77
	ds_read2_b32 v[18:19], v2 offset0:134 offset1:142
	ds_read2_b32 v[20:21], v2 offset0:199 offset1:207
	s_waitcnt lgkmcnt(3)
	v_bfe_u32 v6, v14, 16, 1
	v_add3_u32 v6, v14, v6, s85
	s_waitcnt lgkmcnt(2)
	v_bfe_u32 v7, v16, 16, 1
	v_lshrrev_b32_e32 v6, 16, v6
	v_add3_u32 v7, v16, v7, s85
	v_and_or_b32 v6, v7, s1, v6
	s_waitcnt lgkmcnt(1)
	v_bfe_u32 v7, v18, 16, 1
	v_add3_u32 v7, v18, v7, s85
	s_waitcnt lgkmcnt(0)
	v_bfe_u32 v8, v20, 16, 1
	v_lshrrev_b32_e32 v7, 16, v7
	v_add3_u32 v8, v20, v8, s85
	v_and_or_b32 v7, v8, s1, v7
	v_or_b32_e32 v8, s10, v73
	v_lshlrev_b32_e32 v208, 12, v8
	v_lshl_add_u64 v[22:23], v[0:1], 0, v[208:209]
	global_store_dwordx4 v[22:23], v[4:7], off
	s_nop 1
	v_bfe_u32 v4, v9, 16, 1
	v_add3_u32 v4, v9, v4, s85
	v_bfe_u32 v5, v3, 16, 1
	v_lshrrev_b32_e32 v4, 16, v4
	v_add3_u32 v3, v3, v5, s85
	v_and_or_b32 v4, v3, s1, v4
	v_bfe_u32 v3, v11, 16, 1
	v_add3_u32 v3, v11, v3, s85
	v_bfe_u32 v5, v13, 16, 1
	v_lshrrev_b32_e32 v3, 16, v3
	v_add3_u32 v5, v13, v5, s85
	v_and_or_b32 v5, v5, s1, v3
	v_bfe_u32 v3, v15, 16, 1
	v_add3_u32 v3, v15, v3, s85
	v_bfe_u32 v6, v17, 16, 1
	v_lshrrev_b32_e32 v3, 16, v3
	v_add3_u32 v6, v17, v6, s85
	v_and_or_b32 v6, v6, s1, v3
	v_bfe_u32 v3, v19, 16, 1
	v_add3_u32 v3, v19, v3, s85
	v_bfe_u32 v7, v21, 16, 1
	v_lshrrev_b32_e32 v3, 16, v3
	v_add3_u32 v7, v21, v7, s85
	v_and_or_b32 v7, v7, s1, v3
	v_or_b32_e32 v3, s10, v75
	v_lshlrev_b32_e32 v208, 12, v3
	v_lshl_add_u64 v[8:9], v[0:1], 0, v[208:209]
	global_store_dwordx4 v[8:9], v[4:7], off
	ds_read2_b32 v[8:9], v74 offset0:81 offset1:89
	ds_read2_b32 v[10:11], v74 offset0:16 offset1:24
	ds_read2_b32 v[12:13], v74 offset0:146 offset1:154
	ds_read2_b32 v[14:15], v74 offset0:211 offset1:219
	ds_read2_b32 v[16:17], v2 offset0:20 offset1:28
	ds_read2_b32 v[18:19], v2 offset0:85 offset1:93
	ds_read2_b32 v[20:21], v2 offset0:150 offset1:158
	ds_read2_b32 v[22:23], v2 offset0:215 offset1:223
	s_waitcnt lgkmcnt(7)
	v_bfe_u32 v4, v8, 16, 1
	s_waitcnt lgkmcnt(6)
	v_bfe_u32 v3, v10, 16, 1
	v_add3_u32 v3, v10, v3, s85
	v_lshrrev_b32_e32 v3, 16, v3
	v_add3_u32 v4, v8, v4, s85
	v_and_or_b32 v4, v4, s1, v3
	s_waitcnt lgkmcnt(5)
	v_bfe_u32 v3, v12, 16, 1
	v_add3_u32 v3, v12, v3, s85
	s_waitcnt lgkmcnt(4)
	v_bfe_u32 v5, v14, 16, 1
	v_lshrrev_b32_e32 v3, 16, v3
	v_add3_u32 v5, v14, v5, s85
	v_and_or_b32 v5, v5, s1, v3
	s_waitcnt lgkmcnt(3)
	v_bfe_u32 v3, v16, 16, 1
	v_add3_u32 v3, v16, v3, s85
	s_waitcnt lgkmcnt(2)
	v_bfe_u32 v6, v18, 16, 1
	v_lshrrev_b32_e32 v3, 16, v3
	v_add3_u32 v6, v18, v6, s85
	v_and_or_b32 v6, v6, s1, v3
	s_waitcnt lgkmcnt(1)
	v_bfe_u32 v3, v20, 16, 1
	v_add3_u32 v3, v20, v3, s85
	s_waitcnt lgkmcnt(0)
	v_bfe_u32 v7, v22, 16, 1
	v_lshrrev_b32_e32 v3, 16, v3
	v_add3_u32 v7, v22, v7, s85
	v_and_or_b32 v7, v7, s1, v3
	v_or_b32_e32 v3, s10, v76
	v_lshlrev_b32_e32 v208, 12, v3
	v_lshl_add_u64 v[24:25], v[0:1], 0, v[208:209]
	v_bfe_u32 v3, v11, 16, 1
	global_store_dwordx4 v[24:25], v[4:7], off
	v_add3_u32 v3, v11, v3, s85
	v_lshrrev_b32_e32 v3, 16, v3
	v_bfe_u32 v4, v9, 16, 1
	v_add3_u32 v4, v9, v4, s85
	v_and_or_b32 v4, v4, s1, v3
	v_bfe_u32 v3, v13, 16, 1
	v_add3_u32 v3, v13, v3, s85
	v_bfe_u32 v5, v15, 16, 1
	v_lshrrev_b32_e32 v3, 16, v3
	v_add3_u32 v5, v15, v5, s85
	v_and_or_b32 v5, v5, s1, v3
	v_bfe_u32 v3, v17, 16, 1
	v_add3_u32 v3, v17, v3, s85
	v_bfe_u32 v6, v19, 16, 1
	v_lshrrev_b32_e32 v3, 16, v3
	v_add3_u32 v6, v19, v6, s85
	v_and_or_b32 v6, v6, s1, v3
	v_bfe_u32 v3, v21, 16, 1
	v_add3_u32 v3, v21, v3, s85
	v_bfe_u32 v7, v23, 16, 1
	v_lshrrev_b32_e32 v3, 16, v3
	v_add3_u32 v7, v23, v7, s85
	v_and_or_b32 v7, v7, s1, v3
	v_or_b32_e32 v3, s10, v77
	v_lshlrev_b32_e32 v208, 12, v3
	v_lshl_add_u64 v[8:9], v[0:1], 0, v[208:209]
	global_store_dwordx4 v[8:9], v[4:7], off
	ds_read2_b32 v[8:9], v74 offset0:97 offset1:105
	ds_read2_b32 v[10:11], v74 offset0:32 offset1:40
	ds_read2_b32 v[12:13], v74 offset0:162 offset1:170
	ds_read2_b32 v[14:15], v74 offset0:227 offset1:235
	ds_read2_b32 v[16:17], v2 offset0:36 offset1:44
	ds_read2_b32 v[18:19], v2 offset0:101 offset1:109
	ds_read2_b32 v[20:21], v2 offset0:166 offset1:174
	ds_read2_b32 v[22:23], v2 offset0:231 offset1:239
	s_waitcnt lgkmcnt(7)
	v_bfe_u32 v4, v8, 16, 1
	s_waitcnt lgkmcnt(6)
	v_bfe_u32 v3, v10, 16, 1
	v_add3_u32 v3, v10, v3, s85
	v_lshrrev_b32_e32 v3, 16, v3
	v_add3_u32 v4, v8, v4, s85
	v_and_or_b32 v4, v4, s1, v3
	s_waitcnt lgkmcnt(5)
	v_bfe_u32 v3, v12, 16, 1
	v_add3_u32 v3, v12, v3, s85
	s_waitcnt lgkmcnt(4)
	v_bfe_u32 v5, v14, 16, 1
	v_lshrrev_b32_e32 v3, 16, v3
	v_add3_u32 v5, v14, v5, s85
	v_and_or_b32 v5, v5, s1, v3
	s_waitcnt lgkmcnt(3)
	v_bfe_u32 v3, v16, 16, 1
	v_add3_u32 v3, v16, v3, s85
	s_waitcnt lgkmcnt(2)
	v_bfe_u32 v6, v18, 16, 1
	v_lshrrev_b32_e32 v3, 16, v3
	v_add3_u32 v6, v18, v6, s85
	v_and_or_b32 v6, v6, s1, v3
	s_waitcnt lgkmcnt(1)
	v_bfe_u32 v3, v20, 16, 1
	v_add3_u32 v3, v20, v3, s85
	s_waitcnt lgkmcnt(0)
	v_bfe_u32 v7, v22, 16, 1
	v_lshrrev_b32_e32 v3, 16, v3
	v_add3_u32 v7, v22, v7, s85
	v_and_or_b32 v7, v7, s1, v3
	v_or_b32_e32 v3, s10, v78
	v_lshlrev_b32_e32 v208, 12, v3
	v_lshl_add_u64 v[24:25], v[0:1], 0, v[208:209]
	v_bfe_u32 v3, v11, 16, 1
	global_store_dwordx4 v[24:25], v[4:7], off
	v_add3_u32 v3, v11, v3, s85
	v_lshrrev_b32_e32 v3, 16, v3
	v_bfe_u32 v4, v9, 16, 1
	v_add3_u32 v4, v9, v4, s85
	v_and_or_b32 v4, v4, s1, v3
	v_bfe_u32 v3, v13, 16, 1
	v_add3_u32 v3, v13, v3, s85
	v_bfe_u32 v5, v15, 16, 1
	v_lshrrev_b32_e32 v3, 16, v3
	v_add3_u32 v5, v15, v5, s85
	v_and_or_b32 v5, v5, s1, v3
	v_bfe_u32 v3, v17, 16, 1
	v_add3_u32 v3, v17, v3, s85
	v_bfe_u32 v6, v19, 16, 1
	v_lshrrev_b32_e32 v3, 16, v3
	v_add3_u32 v6, v19, v6, s85
	v_and_or_b32 v6, v6, s1, v3
	v_bfe_u32 v3, v21, 16, 1
	v_add3_u32 v3, v21, v3, s85
	v_bfe_u32 v7, v23, 16, 1
	v_lshrrev_b32_e32 v3, 16, v3
	v_add3_u32 v7, v23, v7, s85
	v_and_or_b32 v7, v7, s1, v3
	v_or_b32_e32 v3, s10, v79
	v_lshlrev_b32_e32 v208, 12, v3
	v_lshl_add_u64 v[8:9], v[0:1], 0, v[208:209]
	global_store_dwordx4 v[8:9], v[4:7], off
	ds_read2_b32 v[8:9], v74 offset0:48 offset1:56
	ds_read2_b32 v[10:11], v74 offset0:113 offset1:121
	ds_read2_b32 v[12:13], v74 offset0:178 offset1:186
	ds_read2_b32 v[14:15], v74 offset0:243 offset1:251
	ds_read2_b32 v[16:17], v2 offset0:52 offset1:60
	ds_read2_b32 v[18:19], v2 offset0:117 offset1:125
	ds_read2_b32 v[20:21], v2 offset0:182 offset1:190
	ds_read2_b32 v[22:23], v2 offset0:247 offset1:255
	s_waitcnt lgkmcnt(7)
	v_bfe_u32 v3, v8, 16, 1
	v_add3_u32 v3, v8, v3, s85
	s_waitcnt lgkmcnt(6)
	v_bfe_u32 v4, v10, 16, 1
	v_lshrrev_b32_e32 v3, 16, v3
	v_add3_u32 v4, v10, v4, s85
	v_and_or_b32 v4, v4, s1, v3
	s_waitcnt lgkmcnt(5)
	v_bfe_u32 v3, v12, 16, 1
	v_add3_u32 v3, v12, v3, s85
	s_waitcnt lgkmcnt(4)
	v_bfe_u32 v5, v14, 16, 1
	v_lshrrev_b32_e32 v3, 16, v3
	v_add3_u32 v5, v14, v5, s85
	v_and_or_b32 v5, v5, s1, v3
	s_waitcnt lgkmcnt(3)
	v_bfe_u32 v3, v16, 16, 1
	v_add3_u32 v3, v16, v3, s85
	s_waitcnt lgkmcnt(2)
	v_bfe_u32 v6, v18, 16, 1
	v_lshrrev_b32_e32 v3, 16, v3
	v_add3_u32 v6, v18, v6, s85
	s_waitcnt lgkmcnt(1)
	v_bfe_u32 v2, v20, 16, 1
	v_and_or_b32 v6, v6, s1, v3
	v_add3_u32 v2, v20, v2, s85
	s_waitcnt lgkmcnt(0)
	v_bfe_u32 v3, v22, 16, 1
	v_lshrrev_b32_e32 v2, 16, v2
	v_add3_u32 v3, v22, v3, s85
	v_and_or_b32 v7, v3, s1, v2
	v_or_b32_e32 v2, s10, v80
	v_lshlrev_b32_e32 v208, 12, v2
	v_lshl_add_u64 v[2:3], v[0:1], 0, v[208:209]
	global_store_dwordx4 v[2:3], v[4:7], off
	v_bfe_u32 v2, v9, 16, 1
	v_add3_u32 v2, v9, v2, s85
	v_bfe_u32 v3, v11, 16, 1
	v_lshrrev_b32_e32 v2, 16, v2
	v_add3_u32 v3, v11, v3, s85
	v_and_or_b32 v2, v3, s1, v2
	v_bfe_u32 v3, v13, 16, 1
	v_add3_u32 v3, v13, v3, s85
	v_bfe_u32 v4, v15, 16, 1
	v_lshrrev_b32_e32 v3, 16, v3
	v_add3_u32 v4, v15, v4, s85
	v_and_or_b32 v3, v4, s1, v3
	v_bfe_u32 v4, v17, 16, 1
	v_add3_u32 v4, v17, v4, s85
	v_bfe_u32 v5, v19, 16, 1
	v_lshrrev_b32_e32 v4, 16, v4
	v_add3_u32 v5, v19, v5, s85
	v_and_or_b32 v4, v5, s1, v4
	v_bfe_u32 v5, v21, 16, 1
	v_add3_u32 v5, v21, v5, s85
	v_bfe_u32 v6, v23, 16, 1
	v_lshrrev_b32_e32 v5, 16, v5
	v_add3_u32 v6, v23, v6, s85
	v_and_or_b32 v5, v6, s1, v5
	v_or_b32_e32 v6, s10, v81
	v_lshlrev_b32_e32 v208, 12, v6
	v_lshl_add_u64 v[0:1], v[0:1], 0, v[208:209]
	global_store_dwordx4 v[0:1], v[2:5], off
	s_waitcnt lgkmcnt(0)

.LBB0_999:
	s_load_dwordx2 s[16:17], s[88:89], 0x18
	s_ashr_i32 s10, s12, 11
	s_ashr_i32 s11, s10, 31
	s_lshl_b64 s[12:13], s[10:11], 25
	v_lshlrev_b32_e32 v208, 2, v64
	s_waitcnt lgkmcnt(0)
	s_add_u32 s12, s16, s12
	s_addc_u32 s13, s17, s13
	s_lshl_b32 s16, s14, 6
	s_and_b32 s16, s16, 0xfc0
	s_and_b32 s15, s14, 0x7c0
	s_lshl_b32 s17, s16, 2
	s_add_u32 s12, s12, s17
	v_or_b32_e32 v71, s15, v65
	s_addc_u32 s13, s13, 0
	v_lshl_add_u64 v[52:53], s[12:13], 0, v[208:209]
	v_lshlrev_b32_e32 v208, 14, v71
	v_lshl_add_u64 v[0:1], v[52:53], 0, v[208:209]
	v_or_b32_e32 v2, 0x10000, v208
	v_mov_b32_e32 v3, v209
	v_or_b32_e32 v4, 0x20000, v208
	v_mov_b32_e32 v5, v209
	v_or_b32_e32 v6, 0x30000, v208
	v_mov_b32_e32 v7, v209
	v_or_b32_e32 v12, 0x40000, v208
	v_mov_b32_e32 v13, v209
	v_or_b32_e32 v14, 0x50000, v208
	v_mov_b32_e32 v15, v209
	v_or_b32_e32 v20, 0x60000, v208
	v_mov_b32_e32 v21, v209
	v_or_b32_e32 v22, 0x70000, v208
	v_mov_b32_e32 v23, v209
	v_or_b32_e32 v28, 0x80000, v208
	v_mov_b32_e32 v29, v209
	v_or_b32_e32 v30, 0x90000, v208
	v_mov_b32_e32 v31, v209
	v_or_b32_e32 v36, 0xa0000, v208
	v_mov_b32_e32 v37, v209
	v_or_b32_e32 v38, 0xb0000, v208
	v_mov_b32_e32 v39, v209
	v_or_b32_e32 v44, 0xc0000, v208
	v_mov_b32_e32 v45, v209
	v_or_b32_e32 v46, 0xd0000, v208
	v_mov_b32_e32 v47, v209
	v_or_b32_e32 v54, 0xe0000, v208
	v_mov_b32_e32 v55, v209
	v_or_b32_e32 v208, 0xf0000, v208
	v_lshl_add_u64 v[2:3], v[52:53], 0, v[2:3]
	v_lshl_add_u64 v[4:5], v[52:53], 0, v[4:5]
	v_lshl_add_u64 v[6:7], v[52:53], 0, v[6:7]
	v_lshl_add_u64 v[12:13], v[52:53], 0, v[12:13]
	v_lshl_add_u64 v[14:15], v[52:53], 0, v[14:15]
	v_lshl_add_u64 v[20:21], v[52:53], 0, v[20:21]
	v_lshl_add_u64 v[22:23], v[52:53], 0, v[22:23]
	v_lshl_add_u64 v[28:29], v[52:53], 0, v[28:29]
	v_lshl_add_u64 v[30:31], v[52:53], 0, v[30:31]
	v_lshl_add_u64 v[36:37], v[52:53], 0, v[36:37]
	v_lshl_add_u64 v[38:39], v[52:53], 0, v[38:39]
	v_lshl_add_u64 v[44:45], v[52:53], 0, v[44:45]
	v_lshl_add_u64 v[46:47], v[52:53], 0, v[46:47]
	v_lshl_add_u64 v[54:55], v[52:53], 0, v[54:55]
	v_lshl_add_u64 v[52:53], v[52:53], 0, v[208:209]
	global_load_dwordx4 v[8:11], v[0:1], off
	s_nop 0
	global_load_dwordx4 v[0:3], v[2:3], off
	s_nop 0
	global_load_dwordx4 v[16:19], v[4:5], off
	s_nop 0
	global_load_dwordx4 v[4:7], v[6:7], off
	s_nop 0
	global_load_dwordx4 v[24:27], v[12:13], off
	s_nop 0
	global_load_dwordx4 v[12:15], v[14:15], off
	s_nop 0
	global_load_dwordx4 v[32:35], v[20:21], off
	s_nop 0
	global_load_dwordx4 v[20:23], v[22:23], off
	s_nop 0
	global_load_dwordx4 v[40:43], v[28:29], off
	s_nop 0
	global_load_dwordx4 v[28:31], v[30:31], off
	s_nop 0
	global_load_dwordx4 v[48:51], v[36:37], off
	s_nop 0
	global_load_dwordx4 v[36:39], v[38:39], off
	s_nop 0
	global_load_dwordx4 v[56:59], v[44:45], off
	s_nop 0
	global_load_dwordx4 v[44:47], v[46:47], off
	s_nop 0
	global_load_dwordx4 v[60:63], v[54:55], off
	s_nop 0
	global_load_dwordx4 v[52:55], v[52:53], off
	s_andn2_b64 vcc, exec, s[8:9]
	s_cbranch_vccnz .LBB0_990
	s_mul_i32 s12, s10, 0x1800
	s_ashr_i32 s13, s12, 31
	s_lshl_b64 s[12:13], s[12:13], 2
	s_add_u32 s12, s2, s12
	s_addc_u32 s13, s3, s13
	v_lshlrev_b32_e32 v71, 2, v71
	global_load_dword v160, v71, s[12:13]
	global_load_dword v161, v71, s[12:13] offset:16
	global_load_dword v162, v71, s[12:13] offset:32
	global_load_dword v163, v71, s[12:13] offset:48
	global_load_dword v164, v71, s[12:13] offset:64
	global_load_dword v165, v71, s[12:13] offset:80
	global_load_dword v166, v71, s[12:13] offset:96
	global_load_dword v167, v71, s[12:13] offset:112
	global_load_dword v168, v71, s[12:13] offset:128
	global_load_dword v169, v71, s[12:13] offset:144
	global_load_dword v170, v71, s[12:13] offset:160
	global_load_dword v171, v71, s[12:13] offset:176
	global_load_dword v172, v71, s[12:13] offset:192
	global_load_dword v173, v71, s[12:13] offset:208
	global_load_dword v174, v71, s[12:13] offset:224
	global_load_dword v175, v71, s[12:13] offset:240
	s_waitcnt vmcnt(0)
	v_mov_b32_e32 v82, v160
	s_waitcnt vmcnt(0)
	v_pk_mul_f32 v[10:11], v[10:11], v[82:83] op_sel_hi:[1,0]
	v_pk_mul_f32 v[8:9], v[8:9], v[82:83] op_sel_hi:[1,0]
	v_mov_b32_e32 v82, v161
	s_waitcnt vmcnt(0)
	v_pk_mul_f32 v[2:3], v[2:3], v[82:83] op_sel_hi:[1,0]
	v_pk_mul_f32 v[0:1], v[0:1], v[82:83] op_sel_hi:[1,0]
	v_mov_b32_e32 v82, v162
	s_waitcnt vmcnt(0)
	v_pk_mul_f32 v[18:19], v[18:19], v[82:83] op_sel_hi:[1,0]
	v_pk_mul_f32 v[16:17], v[16:17], v[82:83] op_sel_hi:[1,0]
	v_mov_b32_e32 v82, v163
	s_waitcnt vmcnt(0)
	v_pk_mul_f32 v[6:7], v[6:7], v[82:83] op_sel_hi:[1,0]
	v_pk_mul_f32 v[4:5], v[4:5], v[82:83] op_sel_hi:[1,0]
	v_mov_b32_e32 v82, v164
	s_waitcnt vmcnt(0)
	v_pk_mul_f32 v[26:27], v[26:27], v[82:83] op_sel_hi:[1,0]
	v_pk_mul_f32 v[24:25], v[24:25], v[82:83] op_sel_hi:[1,0]
	v_mov_b32_e32 v82, v165
	s_waitcnt vmcnt(0)
	v_pk_mul_f32 v[14:15], v[14:15], v[82:83] op_sel_hi:[1,0]
	v_pk_mul_f32 v[12:13], v[12:13], v[82:83] op_sel_hi:[1,0]
	v_mov_b32_e32 v82, v166
	s_waitcnt vmcnt(0)
	v_pk_mul_f32 v[34:35], v[34:35], v[82:83] op_sel_hi:[1,0]
	v_pk_mul_f32 v[32:33], v[32:33], v[82:83] op_sel_hi:[1,0]
	v_mov_b32_e32 v82, v167
	s_waitcnt vmcnt(0)
	v_pk_mul_f32 v[22:23], v[22:23], v[82:83] op_sel_hi:[1,0]
	v_pk_mul_f32 v[20:21], v[20:21], v[82:83] op_sel_hi:[1,0]
	v_mov_b32_e32 v82, v168
	s_waitcnt vmcnt(0)
	v_pk_mul_f32 v[42:43], v[42:43], v[82:83] op_sel_hi:[1,0]
	v_pk_mul_f32 v[40:41], v[40:41], v[82:83] op_sel_hi:[1,0]
	v_mov_b32_e32 v82, v169
	s_waitcnt vmcnt(0)
	v_pk_mul_f32 v[30:31], v[30:31], v[82:83] op_sel_hi:[1,0]
	v_pk_mul_f32 v[28:29], v[28:29], v[82:83] op_sel_hi:[1,0]
	v_mov_b32_e32 v82, v170
	s_waitcnt vmcnt(0)
	v_pk_mul_f32 v[50:51], v[50:51], v[82:83] op_sel_hi:[1,0]
	v_pk_mul_f32 v[48:49], v[48:49], v[82:83] op_sel_hi:[1,0]
	v_mov_b32_e32 v82, v171
	s_waitcnt vmcnt(0)
	v_pk_mul_f32 v[38:39], v[38:39], v[82:83] op_sel_hi:[1,0]
	v_pk_mul_f32 v[36:37], v[36:37], v[82:83] op_sel_hi:[1,0]
	v_mov_b32_e32 v82, v172
	s_waitcnt vmcnt(0)
	v_pk_mul_f32 v[58:59], v[58:59], v[82:83] op_sel_hi:[1,0]
	v_pk_mul_f32 v[56:57], v[56:57], v[82:83] op_sel_hi:[1,0]
	v_mov_b32_e32 v82, v173
	s_waitcnt vmcnt(0)
	v_pk_mul_f32 v[46:47], v[46:47], v[82:83] op_sel_hi:[1,0]
	v_pk_mul_f32 v[44:45], v[44:45], v[82:83] op_sel_hi:[1,0]
	v_mov_b32_e32 v82, v174
	s_waitcnt vmcnt(0)
	v_pk_mul_f32 v[62:63], v[62:63], v[82:83] op_sel_hi:[1,0]
	v_pk_mul_f32 v[60:61], v[60:61], v[82:83] op_sel_hi:[1,0]
	v_mov_b32_e32 v82, v175
	s_waitcnt vmcnt(0)
	v_pk_mul_f32 v[54:55], v[54:55], v[82:83] op_sel_hi:[1,0]
	v_pk_mul_f32 v[52:53], v[52:53], v[82:83] op_sel_hi:[1,0]
	s_branch .LBB0_990
